# F4 + every GEMM body: one static priority raise for waves 0-3 (leading wave group), per-phase s_setprio flips deleted
# baseline (speedup 1.0000x reference)
.LBB1_162:
	v_readlane_b32 s1, v255, 43
	s_add_i32 s1, s1, 2
	s_cmp_ge_i32 s1, s77
	s_cbranch_scc1 .LBB1_212
	s_setprio 0
	s_waitcnt vmcnt(0)
	s_barrier
	s_mov_b64 s[2:3], exec
	v_readlane_b32 s6, v255, 20
	v_readlane_b32 s7, v255, 21
	s_and_b64 s[6:7], s[2:3], s[6:7]
	s_mov_b64 exec, s[6:7]
	s_cbranch_execz .LBB1_211
	v_readlane_b32 s5, v255, 18
	s_waitcnt vmcnt(0) expcnt(0) lgkmcnt(0)
	buffer_inv sc1
	s_nop 0
	v_mov_b32_e32 v0, s5
	ds_read_b32 v2, v0
	v_readlane_b32 s5, v255, 19
	s_waitcnt lgkmcnt(0)
	v_cmp_ne_u32_e32 vcc, 0, v2
	v_mov_b32_e32 v0, s5
	ds_read_b32 v0, v0
	s_cbranch_vccnz .LBB1_179
	v_readlane_b32 s10, v253, 8
	v_readlane_b32 s11, v253, 9
	s_load_dwordx2 s[6:7], s[10:11], 0x4
	s_waitcnt lgkmcnt(0)
	s_mul_i32 s5, s6, s33
	s_mul_i32 s5, s5, s7
	s_mov_b32 s6, 1
	s_branch .LBB1_167

.LBB1_218:
	v_mov_b32_e32 v133, v113
	v_lshl_add_u64 v[8:9], s[60:61], 0, v[132:133]
	v_mov_b32_e32 v137, v113
	v_and_b32_e32 v7, 48, v0
	v_lshlrev_b32_e32 v16, 6, v0
	s_movk_i32 s19, 0x3c0
	v_lshlrev_b32_e32 v0, 2, v0
	v_lshl_add_u64 v[10:11], s[60:61], 0, v[136:137]
	v_mov_b32_e32 v131, v113
	s_and_b32 s27, s30, 3
	s_lshl_b32 s18, s26, 13
	v_and_or_b32 v7, v16, s19, v7
	v_and_b32_e32 v0, 32, v0
	s_add_i32 m0, s9, 0x18000
	v_lshl_add_u64 v[8:9], v[8:9], 0, s[48:49]
	v_lshl_add_u64 v[12:13], s[40:41], 0, v[130:131]
	v_mov_b32_e32 v135, v113
	s_lshl_b32 s25, s26, 6
	v_bitop3_b32 v16, v7, s18, v0 bitop3:0xde
	s_lshl_b32 s18, s27, 12
	s_waitcnt vmcnt(2)
	s_barrier
	global_load_lds_dwordx4 v[8:9], off
	v_lshl_add_u64 v[8:9], v[10:11], 0, s[48:49]
	s_add_i32 m0, s9, 0x1a000
	s_add_i32 s54, s9, 0x8000
	s_add_i32 s55, s9, 0xa000
	v_lshl_add_u64 v[14:15], s[40:41], 0, v[134:135]
	v_bitop3_b32 v148, v7, s18, v0 bitop3:0xde
	global_load_lds_dwordx4 v[8:9], off
	v_lshl_add_u64 v[8:9], v[12:13], 0, s[48:49]
	s_mov_b32 m0, s54
	s_add_u32 s18, s60, 0x20080
	global_load_lds_dwordx4 v[8:9], off
	v_lshl_add_u64 v[8:9], v[14:15], 0, s[48:49]
	s_mov_b32 m0, s55
	s_addc_u32 s19, s61, 0
	global_load_lds_dwordx4 v[8:9], off
	s_add_i32 m0, s9, 0x1c000
	v_lshl_add_u64 v[8:9], s[18:19], 0, v[132:133]
	global_load_lds_dwordx4 v[8:9], off
	v_lshl_add_u64 v[8:9], s[18:19], 0, v[136:137]
	s_add_i32 m0, s9, 0x1e000
	v_lshlrev_b32_e32 v0, 15, v1
	global_load_lds_dwordx4 v[8:9], off
	v_and_b32_e32 v0, 0xffff0000, v0
	v_lshl_add_u32 v0, v2, 12, v0
	v_and_b32_e32 v1, 1, v1
	v_lshl_or_b32 v0, v1, 6, v0
	v_lshl_add_u32 v138, v3, 1, v0
	v_lshlrev_b32_e32 v0, 15, v4
	v_and_b32_e32 v0, 0xffff0000, v0
	s_waitcnt vmcnt(6)
	v_lshl_add_u32 v0, v5, 12, v0
	v_and_b32_e32 v1, 1, v4
	s_cmp_lt_u32 s30, 4
	s_cbranch_scc0 .Lgp_0
	s_setprio 1
.Lgp_0:
	v_lshl_or_b32 v0, v1, 6, v0
	s_cselect_b64 s[18:19], -1, 0
	s_lshl_b32 s56, s27, 6
	s_ashr_i32 s57, s1, 31
	v_mov_b32_e32 v139, v113
	v_lshl_add_u32 v140, v6, 1, v0
	v_mov_b32_e32 v141, v113
	s_mov_b32 s66, 0
	v_add_u32_e32 v149, 0, v16
	s_movk_i32 s81, 0xbc
	s_barrier
	s_branch .LBB1_221

.LBB1_224:
	s_add_u32 s60, s40, 0xfff80080
	s_addc_u32 s61, s41, -1
	s_add_i32 s78, 0, 0x10000
	s_cmp_eq_u32 s77, 28
	s_cselect_b32 s63, s27, s61
	s_cselect_b32 s62, s39, s60
	v_add_u32_e32 v112, s78, v148
	s_cselect_b32 s61, s72, s76
	s_cselect_b32 s60, s74, s75
	s_add_i32 s80, 0, 0x14000
	ds_read_b128 v[142:145], v112
	ds_read_b128 v[150:153], v112 offset:1024
	ds_read_b128 v[154:157], v112 offset:2048
	ds_read_b128 v[158:161], v112 offset:3072
	v_add_u32_e32 v112, s80, v148
	ds_read_b128 v[162:165], v112
	ds_read_b128 v[166:169], v112 offset:1024
	ds_read_b128 v[170:173], v112 offset:2048
	ds_read_b128 v[174:177], v112 offset:3072
	v_lshl_add_u64 v[146:147], s[40:41], 0, v[138:139]
	s_add_i32 m0, s9, 0xc000
	ds_read_b128 v[178:181], v149
	ds_read_b128 v[182:185], v149 offset:1024
	ds_read_b128 v[186:189], v149 offset:2048
	ds_read_b128 v[190:193], v149 offset:3072
	ds_read_b128 v[206:209], v149 offset:4096
	ds_read_b128 v[210:213], v149 offset:5120
	ds_read_b128 v[234:237], v149 offset:6144
	ds_read_b128 v[238:241], v149 offset:7168
	global_load_lds_dwordx4 v[146:147], off
	v_lshl_add_u64 v[146:147], s[40:41], 0, v[140:141]
	s_add_i32 m0, s9, 0xe000
	s_nop 0
	global_load_lds_dwordx4 v[146:147], off
	s_waitcnt vmcnt(8)
	s_waitcnt lgkmcnt(0)
	s_barrier
	s_waitcnt lgkmcnt(0)
	v_mfma_f32_16x16x32_bf16 v[126:129], v[142:145], v[178:181], v[126:129]
	v_mfma_f32_16x16x32_bf16 v[122:125], v[154:157], v[178:181], v[122:125]
	v_mfma_f32_16x16x32_bf16 v[108:111], v[142:145], v[186:189], v[108:111]
	v_mfma_f32_16x16x32_bf16 v[104:107], v[154:157], v[186:189], v[104:107]
	v_mfma_f32_16x16x32_bf16 v[92:95], v[142:145], v[206:209], v[92:95]
	v_mfma_f32_16x16x32_bf16 v[88:91], v[154:157], v[206:209], v[88:91]
	v_mfma_f32_16x16x32_bf16 v[76:79], v[142:145], v[234:237], v[76:79]
	v_mfma_f32_16x16x32_bf16 v[72:75], v[154:157], v[234:237], v[72:75]
	v_mfma_f32_16x16x32_bf16 v[126:129], v[150:153], v[182:185], v[126:129]
	v_mfma_f32_16x16x32_bf16 v[122:125], v[158:161], v[182:185], v[122:125]
	v_mfma_f32_16x16x32_bf16 v[108:111], v[150:153], v[190:193], v[108:111]
	v_mfma_f32_16x16x32_bf16 v[104:107], v[158:161], v[190:193], v[104:107]
	v_mfma_f32_16x16x32_bf16 v[92:95], v[150:153], v[210:213], v[92:95]
	v_mfma_f32_16x16x32_bf16 v[88:91], v[158:161], v[210:213], v[88:91]
	v_mfma_f32_16x16x32_bf16 v[76:79], v[150:153], v[238:241], v[76:79]
	v_mfma_f32_16x16x32_bf16 v[72:75], v[158:161], v[238:241], v[72:75]
	v_mfma_f32_16x16x32_bf16 v[118:121], v[162:165], v[178:181], v[118:121]
	v_mfma_f32_16x16x32_bf16 v[114:117], v[170:173], v[178:181], v[114:117]
	v_mfma_f32_16x16x32_bf16 v[100:103], v[162:165], v[186:189], v[100:103]
	v_mfma_f32_16x16x32_bf16 v[96:99], v[170:173], v[186:189], v[96:99]
	v_mfma_f32_16x16x32_bf16 v[84:87], v[162:165], v[206:209], v[84:87]
	v_mfma_f32_16x16x32_bf16 v[80:83], v[170:173], v[206:209], v[80:83]
	v_mfma_f32_16x16x32_bf16 v[68:71], v[162:165], v[234:237], v[68:71]
	v_mfma_f32_16x16x32_bf16 v[64:67], v[170:173], v[234:237], v[64:67]
	v_mfma_f32_16x16x32_bf16 v[118:121], v[166:169], v[182:185], v[118:121]
	v_mfma_f32_16x16x32_bf16 v[114:117], v[174:177], v[182:185], v[114:117]
	v_mfma_f32_16x16x32_bf16 v[100:103], v[166:169], v[190:193], v[100:103]
	v_mfma_f32_16x16x32_bf16 v[96:99], v[174:177], v[190:193], v[96:99]
	v_mfma_f32_16x16x32_bf16 v[84:87], v[166:169], v[210:213], v[84:87]
	v_mfma_f32_16x16x32_bf16 v[80:83], v[174:177], v[210:213], v[80:83]
	v_mfma_f32_16x16x32_bf16 v[68:71], v[166:169], v[238:241], v[68:71]
	v_mfma_f32_16x16x32_bf16 v[64:67], v[174:177], v[238:241], v[64:67]
	s_barrier
	s_add_i32 s78, s78, s7
	v_lshl_add_u64 v[146:147], s[60:61], 0, v[132:133]
	s_mov_b32 m0, s78
	ds_read_b128 v[178:181], v149 offset:16384
	ds_read_b128 v[182:185], v149 offset:17408
	ds_read_b128 v[186:189], v149 offset:18432
	ds_read_b128 v[190:193], v149 offset:19456
	ds_read_b128 v[206:209], v149 offset:20480
	ds_read_b128 v[210:213], v149 offset:21504
	ds_read_b128 v[234:237], v149 offset:22528
	ds_read_b128 v[238:241], v149 offset:23552
	global_load_lds_dwordx4 v[146:147], off
	s_add_i32 m0, s78, 0x2000
	s_add_u32 s78, s60, 0x20000
	v_lshl_add_u64 v[198:199], s[60:61], 0, v[136:137]
	s_addc_u32 s79, s61, 0
	s_add_i32 s80, s80, s7
	global_load_lds_dwordx4 v[198:199], off
	v_lshl_add_u64 v[200:201], s[78:79], 0, v[132:133]
	s_mov_b32 m0, s80
	v_lshl_add_u64 v[242:243], s[62:63], 0, v[134:135]
	global_load_lds_dwordx4 v[200:201], off
	v_lshl_add_u64 v[200:201], s[78:79], 0, v[136:137]
	s_add_i32 m0, s80, 0x2000
	s_nop 0
	global_load_lds_dwordx4 v[200:201], off
	v_lshl_add_u64 v[200:201], s[62:63], 0, v[130:131]
	s_mov_b32 m0, s9
	s_nop 0
	global_load_lds_dwordx4 v[200:201], off
	s_mov_b32 m0, s10
	s_nop 0
	global_load_lds_dwordx4 v[242:243], off
	s_waitcnt vmcnt(8)
	s_waitcnt lgkmcnt(0)
	s_barrier
	s_waitcnt lgkmcnt(0)
	v_mfma_f32_16x16x32_bf16 v[60:63], v[142:145], v[178:181], v[60:63]
	v_mfma_f32_16x16x32_bf16 v[56:59], v[154:157], v[178:181], v[56:59]
	v_mfma_f32_16x16x32_bf16 v[44:47], v[142:145], v[186:189], v[44:47]
	v_mfma_f32_16x16x32_bf16 v[40:43], v[154:157], v[186:189], v[40:43]
	v_mfma_f32_16x16x32_bf16 v[28:31], v[142:145], v[206:209], v[28:31]
	v_mfma_f32_16x16x32_bf16 v[24:27], v[154:157], v[206:209], v[24:27]
	v_mfma_f32_16x16x32_bf16 v[12:15], v[142:145], v[234:237], v[12:15]
	v_mfma_f32_16x16x32_bf16 v[8:11], v[154:157], v[234:237], v[8:11]
	v_mfma_f32_16x16x32_bf16 v[60:63], v[150:153], v[182:185], v[60:63]
	v_mfma_f32_16x16x32_bf16 v[56:59], v[158:161], v[182:185], v[56:59]
	v_mfma_f32_16x16x32_bf16 v[44:47], v[150:153], v[190:193], v[44:47]
	v_mfma_f32_16x16x32_bf16 v[40:43], v[158:161], v[190:193], v[40:43]
	v_mfma_f32_16x16x32_bf16 v[28:31], v[150:153], v[210:213], v[28:31]
	v_mfma_f32_16x16x32_bf16 v[24:27], v[158:161], v[210:213], v[24:27]
	v_mfma_f32_16x16x32_bf16 v[12:15], v[150:153], v[238:241], v[12:15]
	v_mfma_f32_16x16x32_bf16 v[8:11], v[158:161], v[238:241], v[8:11]
	v_mfma_f32_16x16x32_bf16 v[52:55], v[162:165], v[178:181], v[52:55]
	v_mfma_f32_16x16x32_bf16 v[48:51], v[170:173], v[178:181], v[48:51]
	v_mfma_f32_16x16x32_bf16 v[36:39], v[162:165], v[186:189], v[36:39]
	v_mfma_f32_16x16x32_bf16 v[32:35], v[170:173], v[186:189], v[32:35]
	v_mfma_f32_16x16x32_bf16 v[20:23], v[162:165], v[206:209], v[20:23]
	v_mfma_f32_16x16x32_bf16 v[16:19], v[170:173], v[206:209], v[16:19]
	v_mfma_f32_16x16x32_bf16 v[4:7], v[162:165], v[234:237], v[4:7]
	v_mfma_f32_16x16x32_bf16 v[0:3], v[170:173], v[234:237], v[0:3]
	v_mfma_f32_16x16x32_bf16 v[52:55], v[166:169], v[182:185], v[52:55]
	v_mfma_f32_16x16x32_bf16 v[48:51], v[174:177], v[182:185], v[48:51]
	v_mfma_f32_16x16x32_bf16 v[36:39], v[166:169], v[190:193], v[36:39]
	v_mfma_f32_16x16x32_bf16 v[32:35], v[174:177], v[190:193], v[32:35]
	v_mfma_f32_16x16x32_bf16 v[20:23], v[166:169], v[210:213], v[20:23]
	v_mfma_f32_16x16x32_bf16 v[16:19], v[174:177], v[210:213], v[16:19]
	v_mfma_f32_16x16x32_bf16 v[4:7], v[166:169], v[238:241], v[4:7]
	v_mfma_f32_16x16x32_bf16 v[0:3], v[174:177], v[238:241], v[0:3]
	s_barrier
	s_add_i32 s78, 0, 0x18000
	v_add_u32_e32 v112, s78, v148
	s_add_i32 s79, 0, 0x1c000
	ds_read_b128 v[142:145], v112
	ds_read_b128 v[150:153], v112 offset:1024
	ds_read_b128 v[154:157], v112 offset:2048
	ds_read_b128 v[158:161], v112 offset:3072
	v_add_u32_e32 v112, s79, v148
	ds_read_b128 v[162:165], v112
	ds_read_b128 v[166:169], v112 offset:1024
	ds_read_b128 v[170:173], v112 offset:2048
	ds_read_b128 v[174:177], v112 offset:3072
	s_add_u32 s62, s62, 0x80000
	s_addc_u32 s63, s63, 0
	s_mov_b32 m0, s11
	v_lshl_add_u64 v[244:245], s[62:63], 0, v[130:131]
	ds_read_b128 v[178:181], v149 offset:32768
	ds_read_b128 v[182:185], v149 offset:33792
	ds_read_b128 v[186:189], v149 offset:34816
	ds_read_b128 v[190:193], v149 offset:35840
	ds_read_b128 v[206:209], v149 offset:36864
	ds_read_b128 v[210:213], v149 offset:37888
	ds_read_b128 v[234:237], v149 offset:38912
	ds_read_b128 v[238:241], v149 offset:39936
	global_load_lds_dwordx4 v[244:245], off
	v_lshl_add_u64 v[244:245], s[62:63], 0, v[134:135]
	s_mov_b32 m0, s24
	s_nop 0
	global_load_lds_dwordx4 v[244:245], off
	s_waitcnt vmcnt(8)
	s_waitcnt lgkmcnt(0)
	s_barrier
	s_waitcnt lgkmcnt(0)
	v_mfma_f32_16x16x32_bf16 v[126:129], v[142:145], v[178:181], v[126:129]
	v_mfma_f32_16x16x32_bf16 v[122:125], v[154:157], v[178:181], v[122:125]
	v_mfma_f32_16x16x32_bf16 v[108:111], v[142:145], v[186:189], v[108:111]
	v_mfma_f32_16x16x32_bf16 v[104:107], v[154:157], v[186:189], v[104:107]
	v_mfma_f32_16x16x32_bf16 v[92:95], v[142:145], v[206:209], v[92:95]
	v_mfma_f32_16x16x32_bf16 v[88:91], v[154:157], v[206:209], v[88:91]
	v_mfma_f32_16x16x32_bf16 v[76:79], v[142:145], v[234:237], v[76:79]
	v_mfma_f32_16x16x32_bf16 v[72:75], v[154:157], v[234:237], v[72:75]
	v_mfma_f32_16x16x32_bf16 v[126:129], v[150:153], v[182:185], v[126:129]
	v_mfma_f32_16x16x32_bf16 v[122:125], v[158:161], v[182:185], v[122:125]
	v_mfma_f32_16x16x32_bf16 v[108:111], v[150:153], v[190:193], v[108:111]
	v_mfma_f32_16x16x32_bf16 v[104:107], v[158:161], v[190:193], v[104:107]
	v_mfma_f32_16x16x32_bf16 v[92:95], v[150:153], v[210:213], v[92:95]
	v_mfma_f32_16x16x32_bf16 v[88:91], v[158:161], v[210:213], v[88:91]
	v_mfma_f32_16x16x32_bf16 v[76:79], v[150:153], v[238:241], v[76:79]
	v_mfma_f32_16x16x32_bf16 v[72:75], v[158:161], v[238:241], v[72:75]
	v_mfma_f32_16x16x32_bf16 v[118:121], v[162:165], v[178:181], v[118:121]
	v_mfma_f32_16x16x32_bf16 v[114:117], v[170:173], v[178:181], v[114:117]
	v_mfma_f32_16x16x32_bf16 v[100:103], v[162:165], v[186:189], v[100:103]
	v_mfma_f32_16x16x32_bf16 v[96:99], v[170:173], v[186:189], v[96:99]
	v_mfma_f32_16x16x32_bf16 v[84:87], v[162:165], v[206:209], v[84:87]
	v_mfma_f32_16x16x32_bf16 v[80:83], v[170:173], v[206:209], v[80:83]
	v_mfma_f32_16x16x32_bf16 v[68:71], v[162:165], v[234:237], v[68:71]
	v_mfma_f32_16x16x32_bf16 v[64:67], v[170:173], v[234:237], v[64:67]
	v_mfma_f32_16x16x32_bf16 v[118:121], v[166:169], v[182:185], v[118:121]
	v_mfma_f32_16x16x32_bf16 v[114:117], v[174:177], v[182:185], v[114:117]
	v_mfma_f32_16x16x32_bf16 v[100:103], v[166:169], v[190:193], v[100:103]
	v_mfma_f32_16x16x32_bf16 v[96:99], v[174:177], v[190:193], v[96:99]
	v_mfma_f32_16x16x32_bf16 v[84:87], v[166:169], v[210:213], v[84:87]
	v_mfma_f32_16x16x32_bf16 v[80:83], v[174:177], v[210:213], v[80:83]
	v_mfma_f32_16x16x32_bf16 v[68:71], v[166:169], v[238:241], v[68:71]
	v_mfma_f32_16x16x32_bf16 v[64:67], v[174:177], v[238:241], v[64:67]
	s_barrier
	s_add_i32 s62, s78, s7
	v_lshl_add_u64 v[146:147], v[146:147], 0, s[48:49]
	s_mov_b32 m0, s62
	ds_read_b128 v[178:181], v149 offset:49152
	ds_read_b128 v[182:185], v149 offset:50176
	ds_read_b128 v[186:189], v149 offset:51200
	ds_read_b128 v[190:193], v149 offset:52224
	ds_read_b128 v[206:209], v149 offset:53248
	ds_read_b128 v[210:213], v149 offset:54272
	ds_read_b128 v[234:237], v149 offset:55296
	ds_read_b128 v[238:241], v149 offset:56320
	global_load_lds_dwordx4 v[146:147], off
	s_add_i32 m0, s62, 0x2000
	s_add_u32 s60, s60, 0x20080
	v_lshl_add_u64 v[146:147], v[198:199], 0, s[48:49]
	s_addc_u32 s61, s61, 0
	s_add_i32 s62, s79, s7
	global_load_lds_dwordx4 v[146:147], off
	v_lshl_add_u64 v[146:147], s[60:61], 0, v[132:133]
	s_mov_b32 m0, s62
	s_nop 0
	global_load_lds_dwordx4 v[146:147], off
	v_lshl_add_u64 v[146:147], s[60:61], 0, v[136:137]
	s_add_i32 m0, s62, 0x2000
	s_nop 0
	global_load_lds_dwordx4 v[146:147], off
	v_lshl_add_u64 v[146:147], v[200:201], 0, s[48:49]
	s_mov_b32 m0, s54
	s_nop 0
	global_load_lds_dwordx4 v[146:147], off
	v_lshl_add_u64 v[146:147], v[242:243], 0, s[48:49]
	s_mov_b32 m0, s55
	s_nop 0
	global_load_lds_dwordx4 v[146:147], off
	s_waitcnt vmcnt(8)
	s_waitcnt lgkmcnt(0)
	s_barrier
	s_waitcnt lgkmcnt(0)
	v_mfma_f32_16x16x32_bf16 v[60:63], v[142:145], v[178:181], v[60:63]
	v_mfma_f32_16x16x32_bf16 v[56:59], v[154:157], v[178:181], v[56:59]
	v_mfma_f32_16x16x32_bf16 v[44:47], v[142:145], v[186:189], v[44:47]
	v_mfma_f32_16x16x32_bf16 v[40:43], v[154:157], v[186:189], v[40:43]
	v_mfma_f32_16x16x32_bf16 v[28:31], v[142:145], v[206:209], v[28:31]
	v_mfma_f32_16x16x32_bf16 v[24:27], v[154:157], v[206:209], v[24:27]
	v_mfma_f32_16x16x32_bf16 v[12:15], v[142:145], v[234:237], v[12:15]
	v_mfma_f32_16x16x32_bf16 v[8:11], v[154:157], v[234:237], v[8:11]
	v_mfma_f32_16x16x32_bf16 v[60:63], v[150:153], v[182:185], v[60:63]
	v_mfma_f32_16x16x32_bf16 v[56:59], v[158:161], v[182:185], v[56:59]
	v_mfma_f32_16x16x32_bf16 v[44:47], v[150:153], v[190:193], v[44:47]
	v_mfma_f32_16x16x32_bf16 v[40:43], v[158:161], v[190:193], v[40:43]
	v_mfma_f32_16x16x32_bf16 v[28:31], v[150:153], v[210:213], v[28:31]
	v_mfma_f32_16x16x32_bf16 v[24:27], v[158:161], v[210:213], v[24:27]
	v_mfma_f32_16x16x32_bf16 v[12:15], v[150:153], v[238:241], v[12:15]
	v_mfma_f32_16x16x32_bf16 v[8:11], v[158:161], v[238:241], v[8:11]
	v_mfma_f32_16x16x32_bf16 v[52:55], v[162:165], v[178:181], v[52:55]
	v_mfma_f32_16x16x32_bf16 v[48:51], v[170:173], v[178:181], v[48:51]
	v_mfma_f32_16x16x32_bf16 v[36:39], v[162:165], v[186:189], v[36:39]
	v_mfma_f32_16x16x32_bf16 v[32:35], v[170:173], v[186:189], v[32:35]
	v_mfma_f32_16x16x32_bf16 v[20:23], v[162:165], v[206:209], v[20:23]
	v_mfma_f32_16x16x32_bf16 v[16:19], v[170:173], v[206:209], v[16:19]
	v_mfma_f32_16x16x32_bf16 v[4:7], v[162:165], v[234:237], v[4:7]
	v_mfma_f32_16x16x32_bf16 v[0:3], v[170:173], v[234:237], v[0:3]
	v_mfma_f32_16x16x32_bf16 v[52:55], v[166:169], v[182:185], v[52:55]
	v_mfma_f32_16x16x32_bf16 v[48:51], v[174:177], v[182:185], v[48:51]
	v_mfma_f32_16x16x32_bf16 v[36:39], v[166:169], v[190:193], v[36:39]
	v_mfma_f32_16x16x32_bf16 v[32:35], v[174:177], v[190:193], v[32:35]
	v_mfma_f32_16x16x32_bf16 v[20:23], v[166:169], v[210:213], v[20:23]
	v_mfma_f32_16x16x32_bf16 v[16:19], v[174:177], v[210:213], v[16:19]
	v_mfma_f32_16x16x32_bf16 v[4:7], v[166:169], v[238:241], v[4:7]
	v_mfma_f32_16x16x32_bf16 v[0:3], v[174:177], v[238:241], v[0:3]
	s_barrier
	s_add_i32 s77, s77, 2
	s_add_u32 s40, s40, 0x100
	s_addc_u32 s41, s41, 0
	s_add_u32 s75, s75, 0x100
	s_addc_u32 s76, s76, 0
	s_cmp_gt_u32 s77, 29
	s_cbranch_scc0 .LBB1_224
	s_and_b64 vcc, exec, s[18:19]
	s_cbranch_vccz .LBB1_227
	s_barrier

.LBB1_295:
	v_readlane_b32 s1, v255, 43
	s_add_i32 s1, s1, 3
	s_cmp_lt_i32 s1, s77
	s_cselect_b64 s[16:17], -1, 0
	s_and_b64 s[2:3], s[2:3], s[16:17]
	s_andn2_b64 vcc, exec, s[2:3]
	s_cbranch_vccnz .LBB1_345
	s_setprio 0
	s_waitcnt vmcnt(0)
	s_waitcnt vmcnt(0)
	s_barrier
	s_mov_b64 s[2:3], exec
	v_readlane_b32 s6, v255, 20
	v_readlane_b32 s7, v255, 21
	s_and_b64 s[6:7], s[2:3], s[6:7]
	s_mov_b64 exec, s[6:7]
	s_cbranch_execz .LBB1_344
	v_readlane_b32 s5, v255, 18
	s_waitcnt vmcnt(0) expcnt(0) lgkmcnt(0)
	buffer_inv sc1
	s_nop 0
	v_mov_b32_e32 v0, s5
	ds_read_b32 v2, v0
	v_readlane_b32 s5, v255, 19
	s_waitcnt lgkmcnt(0)
	v_cmp_ne_u32_e32 vcc, 0, v2
	v_mov_b32_e32 v0, s5
	ds_read_b32 v0, v0
	s_cbranch_vccnz .LBB1_312
	v_readlane_b32 s10, v253, 8
	v_readlane_b32 s11, v253, 9
	s_load_dwordx2 s[6:7], s[10:11], 0x4
	s_waitcnt lgkmcnt(0)
	s_mul_i32 s5, s6, s33
	s_mul_i32 s5, s5, s7
	s_mov_b32 s6, 1
	s_branch .LBB1_300

.LBB1_385:
	s_sext_i32_i8 s66, s16
	s_lshl_b32 s24, s18, 6
	v_and_b32_e32 v1, 48, v0
	s_lshl_b32 s16, s18, 13
	v_lshlrev_b32_e32 v6, 6, v0
	s_movk_i32 s18, 0x3c0
	v_lshlrev_b32_e32 v0, 2, v0
	s_and_b32 s26, s17, 3
	v_and_or_b32 v1, v6, s18, v1
	v_and_b32_e32 v0, 32, v0
	v_lshl_add_u64 v[2:3], s[38:39], 0, v[112:113]
	v_mov_b32_e32 v135, v113
	v_bitop3_b32 v6, v1, s16, v0 bitop3:0xde
	s_lshl_b32 s16, s26, 12
	v_lshl_add_u64 v[4:5], s[38:39], 0, v[134:135]
	v_bitop3_b32 v136, v1, s16, v0 bitop3:0xde
	s_add_i32 m0, s7, 0x18000
	v_lshl_add_u64 v[0:1], v[2:3], 0, s[48:49]
	v_readlane_b32 s18, v254, 42
	v_mov_b32_e32 v131, v113
	s_waitcnt vmcnt(2)
	s_barrier
	global_load_lds_dwordx4 v[0:1], off
	v_lshl_add_u64 v[0:1], v[4:5], 0, s[48:49]
	s_add_i32 m0, s7, 0x1a000
	v_readlane_b32 s19, v254, 43
	s_add_i32 s25, s7, 0x8000
	v_mov_b32_e32 v133, v113
	global_load_lds_dwordx4 v[0:1], off
	v_lshl_add_u64 v[0:1], s[18:19], 0, v[130:131]
	s_mov_b32 m0, s25
	s_add_i32 s54, s7, 0xa000
	global_load_lds_dwordx4 v[0:1], off
	v_lshl_add_u64 v[0:1], s[18:19], 0, v[132:133]
	s_add_u32 s18, s38, 0xb0080
	s_mov_b32 m0, s54
	s_addc_u32 s19, s39, 0
	global_load_lds_dwordx4 v[0:1], off
	s_add_i32 m0, s7, 0x1c000
	v_lshl_add_u64 v[0:1], s[18:19], 0, v[112:113]
	global_load_lds_dwordx4 v[0:1], off
	v_lshl_add_u64 v[0:1], s[18:19], 0, v[134:135]
	s_add_i32 m0, s7, 0x1e000
	s_cmp_lt_u32 s17, 4
	s_cbranch_scc0 .Lgp_1
	s_setprio 1
.Lgp_1:
	global_load_lds_dwordx4 v[0:1], off
	s_waitcnt vmcnt(6)
	s_cselect_b64 s[16:17], -1, 0
	s_lshl_b32 s56, s26, 6
	s_mov_b32 s57, 0
	v_add_u32_e32 v137, 0, v6
	s_barrier
	s_branch .LBB1_388

.LBB1_395:
	s_add_i32 s45, s44, 0x100
	s_and_b64 s[58:59], s[42:43], exec
	s_cselect_b32 s45, 0, s45
	s_cselect_b32 s59, 0, 0
	s_add_u32 s58, s50, s45
	s_addc_u32 s59, s51, s59
	s_add_u32 s45, s38, s44
	s_addc_u32 s60, s39, 0
	s_add_u32 s45, s45, 0x100
	s_addc_u32 s60, s60, 0
	s_add_i32 s83, 0, 0x10000
	s_and_b64 s[42:43], s[42:43], exec
	s_cselect_b32 s61, s67, s60
	s_cselect_b32 s60, s68, s45
	s_add_i32 s43, 0, 0x14000
	s_add_u32 s42, s22, s44
	s_addc_u32 s44, s23, 0
	s_add_u32 s74, s42, 0x520080
	s_addc_u32 s75, s44, 0
	s_add_i32 s82, s83, s6
	s_add_i32 m0, s7, 0xc000
	s_add_i32 s85, s7, 0xe000
	s_add_i32 s79, s82, 0x2000
	s_add_u32 s62, s60, 0xb0000
	v_add_u32_e32 v150, s83, v136
	v_add_u32_e32 v166, s43, v136
	s_addc_u32 s63, s61, 0
	s_add_i32 s81, s43, s6
	ds_read_b128 v[138:141], v150
	ds_read_b128 v[142:145], v150 offset:1024
	ds_read_b128 v[146:149], v150 offset:2048
	ds_read_b128 v[150:153], v150 offset:3072
	ds_read_b128 v[154:157], v166
	ds_read_b128 v[158:161], v166 offset:1024
	ds_read_b128 v[162:165], v166 offset:2048
	ds_read_b128 v[166:169], v166 offset:3072
	s_add_i32 s80, s81, 0x2000
	s_add_i32 s78, 0, 0x18000
	s_add_i32 s77, 0, 0x1c000
	s_add_u32 s44, s58, 0x10000
	s_addc_u32 s45, s59, 0
	s_add_i32 s76, s78, s6
	s_add_i32 s72, s76, 0x2000
	s_add_u32 s42, s60, 0xb0080
	s_addc_u32 s43, s61, 0
	s_add_i32 s84, s77, s6
	s_add_i32 s83, s84, 0x2000
	v_lshl_add_u64 v[198:199], s[74:75], 0, v[130:131]
	ds_read_b128 v[170:173], v137
	ds_read_b128 v[174:177], v137 offset:1024
	ds_read_b128 v[178:181], v137 offset:2048
	ds_read_b128 v[182:185], v137 offset:3072
	ds_read_b128 v[186:189], v137 offset:4096
	ds_read_b128 v[190:193], v137 offset:5120
	ds_read_b128 v[206:209], v137 offset:6144
	ds_read_b128 v[210:213], v137 offset:7168
	global_load_lds_dwordx4 v[198:199], off
	v_lshl_add_u64 v[198:199], s[74:75], 0, v[132:133]
	s_mov_b32 m0, s85
	s_nop 0
	global_load_lds_dwordx4 v[198:199], off
	s_waitcnt vmcnt(8)
	s_waitcnt lgkmcnt(0)
	s_barrier
	s_waitcnt lgkmcnt(0)
	v_mfma_f32_16x16x32_bf16 v[126:129], v[138:141], v[170:173], v[126:129]
	v_mfma_f32_16x16x32_bf16 v[122:125], v[146:149], v[170:173], v[122:125]
	v_mfma_f32_16x16x32_bf16 v[118:121], v[138:141], v[178:181], v[118:121]
	v_mfma_f32_16x16x32_bf16 v[114:117], v[146:149], v[178:181], v[114:117]
	v_mfma_f32_16x16x32_bf16 v[100:103], v[138:141], v[186:189], v[100:103]
	v_mfma_f32_16x16x32_bf16 v[96:99], v[146:149], v[186:189], v[96:99]
	v_mfma_f32_16x16x32_bf16 v[84:87], v[138:141], v[206:209], v[84:87]
	v_mfma_f32_16x16x32_bf16 v[80:83], v[146:149], v[206:209], v[80:83]
	v_mfma_f32_16x16x32_bf16 v[126:129], v[142:145], v[174:177], v[126:129]
	v_mfma_f32_16x16x32_bf16 v[122:125], v[150:153], v[174:177], v[122:125]
	v_mfma_f32_16x16x32_bf16 v[118:121], v[142:145], v[182:185], v[118:121]
	v_mfma_f32_16x16x32_bf16 v[114:117], v[150:153], v[182:185], v[114:117]
	v_mfma_f32_16x16x32_bf16 v[100:103], v[142:145], v[190:193], v[100:103]
	v_mfma_f32_16x16x32_bf16 v[96:99], v[150:153], v[190:193], v[96:99]
	v_mfma_f32_16x16x32_bf16 v[84:87], v[142:145], v[210:213], v[84:87]
	v_mfma_f32_16x16x32_bf16 v[80:83], v[150:153], v[210:213], v[80:83]
	v_mfma_f32_16x16x32_bf16 v[108:111], v[154:157], v[170:173], v[108:111]
	v_mfma_f32_16x16x32_bf16 v[104:107], v[162:165], v[170:173], v[104:107]
	v_mfma_f32_16x16x32_bf16 v[92:95], v[154:157], v[178:181], v[92:95]
	v_mfma_f32_16x16x32_bf16 v[88:91], v[162:165], v[178:181], v[88:91]
	v_mfma_f32_16x16x32_bf16 v[76:79], v[154:157], v[186:189], v[76:79]
	v_mfma_f32_16x16x32_bf16 v[72:75], v[162:165], v[186:189], v[72:75]
	v_mfma_f32_16x16x32_bf16 v[68:71], v[154:157], v[206:209], v[68:71]
	v_mfma_f32_16x16x32_bf16 v[64:67], v[162:165], v[206:209], v[64:67]
	v_mfma_f32_16x16x32_bf16 v[108:111], v[158:161], v[174:177], v[108:111]
	v_mfma_f32_16x16x32_bf16 v[104:107], v[166:169], v[174:177], v[104:107]
	v_mfma_f32_16x16x32_bf16 v[92:95], v[158:161], v[182:185], v[92:95]
	v_mfma_f32_16x16x32_bf16 v[88:91], v[166:169], v[182:185], v[88:91]
	v_mfma_f32_16x16x32_bf16 v[76:79], v[158:161], v[190:193], v[76:79]
	v_mfma_f32_16x16x32_bf16 v[72:75], v[166:169], v[190:193], v[72:75]
	v_mfma_f32_16x16x32_bf16 v[68:71], v[158:161], v[210:213], v[68:71]
	v_mfma_f32_16x16x32_bf16 v[64:67], v[166:169], v[210:213], v[64:67]
	s_barrier
	s_mov_b32 m0, s82
	v_lshl_add_u64 v[198:199], s[60:61], 0, v[112:113]
	ds_read_b128 v[170:173], v137 offset:16384
	ds_read_b128 v[174:177], v137 offset:17408
	ds_read_b128 v[178:181], v137 offset:18432
	ds_read_b128 v[182:185], v137 offset:19456
	ds_read_b128 v[186:189], v137 offset:20480
	ds_read_b128 v[190:193], v137 offset:21504
	ds_read_b128 v[206:209], v137 offset:22528
	ds_read_b128 v[210:213], v137 offset:23552
	global_load_lds_dwordx4 v[198:199], off
	v_lshl_add_u64 v[200:201], s[60:61], 0, v[134:135]
	s_mov_b32 m0, s79
	v_lshl_add_u64 v[234:235], s[62:63], 0, v[112:113]
	global_load_lds_dwordx4 v[200:201], off
	s_mov_b32 m0, s81
	v_lshl_add_u64 v[236:237], s[58:59], 0, v[132:133]
	global_load_lds_dwordx4 v[234:235], off
	v_lshl_add_u64 v[234:235], s[62:63], 0, v[134:135]
	s_mov_b32 m0, s80
	s_nop 0
	global_load_lds_dwordx4 v[234:235], off
	v_lshl_add_u64 v[234:235], s[58:59], 0, v[130:131]
	s_mov_b32 m0, s7
	s_nop 0
	global_load_lds_dwordx4 v[234:235], off
	s_mov_b32 m0, s9
	s_nop 0
	global_load_lds_dwordx4 v[236:237], off
	s_waitcnt vmcnt(8)
	s_waitcnt lgkmcnt(0)
	s_barrier
	s_waitcnt lgkmcnt(0)
	v_mfma_f32_16x16x32_bf16 v[60:63], v[138:141], v[170:173], v[60:63]
	v_mfma_f32_16x16x32_bf16 v[56:59], v[146:149], v[170:173], v[56:59]
	v_mfma_f32_16x16x32_bf16 v[52:55], v[138:141], v[178:181], v[52:55]
	v_mfma_f32_16x16x32_bf16 v[48:51], v[146:149], v[178:181], v[48:51]
	v_mfma_f32_16x16x32_bf16 v[36:39], v[138:141], v[186:189], v[36:39]
	v_mfma_f32_16x16x32_bf16 v[32:35], v[146:149], v[186:189], v[32:35]
	v_mfma_f32_16x16x32_bf16 v[20:23], v[138:141], v[206:209], v[20:23]
	v_mfma_f32_16x16x32_bf16 v[16:19], v[146:149], v[206:209], v[16:19]
	v_mfma_f32_16x16x32_bf16 v[60:63], v[142:145], v[174:177], v[60:63]
	v_mfma_f32_16x16x32_bf16 v[56:59], v[150:153], v[174:177], v[56:59]
	v_mfma_f32_16x16x32_bf16 v[52:55], v[142:145], v[182:185], v[52:55]
	v_mfma_f32_16x16x32_bf16 v[48:51], v[150:153], v[182:185], v[48:51]
	v_mfma_f32_16x16x32_bf16 v[36:39], v[142:145], v[190:193], v[36:39]
	v_mfma_f32_16x16x32_bf16 v[32:35], v[150:153], v[190:193], v[32:35]
	v_mfma_f32_16x16x32_bf16 v[20:23], v[142:145], v[210:213], v[20:23]
	v_mfma_f32_16x16x32_bf16 v[16:19], v[150:153], v[210:213], v[16:19]
	v_mfma_f32_16x16x32_bf16 v[44:47], v[154:157], v[170:173], v[44:47]
	v_mfma_f32_16x16x32_bf16 v[40:43], v[162:165], v[170:173], v[40:43]
	v_mfma_f32_16x16x32_bf16 v[28:31], v[154:157], v[178:181], v[28:31]
	v_mfma_f32_16x16x32_bf16 v[24:27], v[162:165], v[178:181], v[24:27]
	v_mfma_f32_16x16x32_bf16 v[12:15], v[154:157], v[186:189], v[12:15]
	v_mfma_f32_16x16x32_bf16 v[8:11], v[162:165], v[186:189], v[8:11]
	v_mfma_f32_16x16x32_bf16 v[4:7], v[154:157], v[206:209], v[4:7]
	v_mfma_f32_16x16x32_bf16 v[0:3], v[162:165], v[206:209], v[0:3]
	v_mfma_f32_16x16x32_bf16 v[44:47], v[158:161], v[174:177], v[44:47]
	v_mfma_f32_16x16x32_bf16 v[40:43], v[166:169], v[174:177], v[40:43]
	v_mfma_f32_16x16x32_bf16 v[28:31], v[158:161], v[182:185], v[28:31]
	v_mfma_f32_16x16x32_bf16 v[24:27], v[166:169], v[182:185], v[24:27]
	v_mfma_f32_16x16x32_bf16 v[12:15], v[158:161], v[190:193], v[12:15]
	v_mfma_f32_16x16x32_bf16 v[8:11], v[166:169], v[190:193], v[8:11]
	v_mfma_f32_16x16x32_bf16 v[4:7], v[158:161], v[210:213], v[4:7]
	v_mfma_f32_16x16x32_bf16 v[0:3], v[166:169], v[210:213], v[0:3]
	s_barrier
	v_add_u32_e32 v150, s78, v136
	v_add_u32_e32 v166, s77, v136
	ds_read_b128 v[138:141], v150
	ds_read_b128 v[142:145], v150 offset:1024
	ds_read_b128 v[146:149], v150 offset:2048
	ds_read_b128 v[150:153], v150 offset:3072
	ds_read_b128 v[154:157], v166
	ds_read_b128 v[158:161], v166 offset:1024
	ds_read_b128 v[162:165], v166 offset:2048
	ds_read_b128 v[166:169], v166 offset:3072
	s_mov_b32 m0, s10
	v_lshl_add_u64 v[238:239], s[44:45], 0, v[130:131]
	ds_read_b128 v[170:173], v137 offset:32768
	ds_read_b128 v[174:177], v137 offset:33792
	ds_read_b128 v[178:181], v137 offset:34816
	ds_read_b128 v[182:185], v137 offset:35840
	ds_read_b128 v[186:189], v137 offset:36864
	ds_read_b128 v[190:193], v137 offset:37888
	ds_read_b128 v[206:209], v137 offset:38912
	ds_read_b128 v[210:213], v137 offset:39936
	global_load_lds_dwordx4 v[238:239], off
	v_lshl_add_u64 v[238:239], s[44:45], 0, v[132:133]
	s_mov_b32 m0, s11
	s_nop 0
	global_load_lds_dwordx4 v[238:239], off
	s_waitcnt vmcnt(8)
	s_waitcnt lgkmcnt(0)
	s_barrier
	s_waitcnt lgkmcnt(0)
	v_mfma_f32_16x16x32_bf16 v[126:129], v[138:141], v[170:173], v[126:129]
	v_mfma_f32_16x16x32_bf16 v[122:125], v[146:149], v[170:173], v[122:125]
	v_mfma_f32_16x16x32_bf16 v[118:121], v[138:141], v[178:181], v[118:121]
	v_mfma_f32_16x16x32_bf16 v[114:117], v[146:149], v[178:181], v[114:117]
	v_mfma_f32_16x16x32_bf16 v[100:103], v[138:141], v[186:189], v[100:103]
	v_mfma_f32_16x16x32_bf16 v[96:99], v[146:149], v[186:189], v[96:99]
	v_mfma_f32_16x16x32_bf16 v[84:87], v[138:141], v[206:209], v[84:87]
	v_mfma_f32_16x16x32_bf16 v[80:83], v[146:149], v[206:209], v[80:83]
	v_mfma_f32_16x16x32_bf16 v[126:129], v[142:145], v[174:177], v[126:129]
	v_mfma_f32_16x16x32_bf16 v[122:125], v[150:153], v[174:177], v[122:125]
	v_mfma_f32_16x16x32_bf16 v[118:121], v[142:145], v[182:185], v[118:121]
	v_mfma_f32_16x16x32_bf16 v[114:117], v[150:153], v[182:185], v[114:117]
	v_mfma_f32_16x16x32_bf16 v[100:103], v[142:145], v[190:193], v[100:103]
	v_mfma_f32_16x16x32_bf16 v[96:99], v[150:153], v[190:193], v[96:99]
	v_mfma_f32_16x16x32_bf16 v[84:87], v[142:145], v[210:213], v[84:87]
	v_mfma_f32_16x16x32_bf16 v[80:83], v[150:153], v[210:213], v[80:83]
	v_mfma_f32_16x16x32_bf16 v[108:111], v[154:157], v[170:173], v[108:111]
	v_mfma_f32_16x16x32_bf16 v[104:107], v[162:165], v[170:173], v[104:107]
	v_mfma_f32_16x16x32_bf16 v[92:95], v[154:157], v[178:181], v[92:95]
	v_mfma_f32_16x16x32_bf16 v[88:91], v[162:165], v[178:181], v[88:91]
	v_mfma_f32_16x16x32_bf16 v[76:79], v[154:157], v[186:189], v[76:79]
	v_mfma_f32_16x16x32_bf16 v[72:75], v[162:165], v[186:189], v[72:75]
	v_mfma_f32_16x16x32_bf16 v[68:71], v[154:157], v[206:209], v[68:71]
	v_mfma_f32_16x16x32_bf16 v[64:67], v[162:165], v[206:209], v[64:67]
	v_mfma_f32_16x16x32_bf16 v[108:111], v[158:161], v[174:177], v[108:111]
	v_mfma_f32_16x16x32_bf16 v[104:107], v[166:169], v[174:177], v[104:107]
	v_mfma_f32_16x16x32_bf16 v[92:95], v[158:161], v[182:185], v[92:95]
	v_mfma_f32_16x16x32_bf16 v[88:91], v[166:169], v[182:185], v[88:91]
	v_mfma_f32_16x16x32_bf16 v[76:79], v[158:161], v[190:193], v[76:79]
	v_mfma_f32_16x16x32_bf16 v[72:75], v[166:169], v[190:193], v[72:75]
	v_mfma_f32_16x16x32_bf16 v[68:71], v[158:161], v[210:213], v[68:71]
	v_mfma_f32_16x16x32_bf16 v[64:67], v[166:169], v[210:213], v[64:67]
	s_barrier
	s_mov_b32 m0, s76
	v_lshl_add_u64 v[198:199], v[198:199], 0, s[48:49]
	ds_read_b128 v[170:173], v137 offset:49152
	ds_read_b128 v[174:177], v137 offset:50176
	ds_read_b128 v[178:181], v137 offset:51200
	ds_read_b128 v[182:185], v137 offset:52224
	ds_read_b128 v[186:189], v137 offset:53248
	ds_read_b128 v[190:193], v137 offset:54272
	ds_read_b128 v[206:209], v137 offset:55296
	ds_read_b128 v[210:213], v137 offset:56320
	global_load_lds_dwordx4 v[198:199], off
	v_lshl_add_u64 v[198:199], v[200:201], 0, s[48:49]
	s_mov_b32 m0, s72
	s_nop 0
	global_load_lds_dwordx4 v[198:199], off
	v_lshl_add_u64 v[198:199], s[42:43], 0, v[112:113]
	s_mov_b32 m0, s84
	s_nop 0
	global_load_lds_dwordx4 v[198:199], off
	v_lshl_add_u64 v[198:199], s[42:43], 0, v[134:135]
	s_mov_b32 m0, s83
	s_nop 0
	global_load_lds_dwordx4 v[198:199], off
	v_lshl_add_u64 v[198:199], v[234:235], 0, s[48:49]
	s_mov_b32 m0, s25
	s_nop 0
	global_load_lds_dwordx4 v[198:199], off
	v_lshl_add_u64 v[198:199], v[236:237], 0, s[48:49]
	s_mov_b32 m0, s54
	s_nop 0
	global_load_lds_dwordx4 v[198:199], off
	s_waitcnt vmcnt(8)
	s_waitcnt lgkmcnt(0)
	s_barrier
	s_waitcnt lgkmcnt(0)
	v_mfma_f32_16x16x32_bf16 v[60:63], v[138:141], v[170:173], v[60:63]
	v_mfma_f32_16x16x32_bf16 v[56:59], v[146:149], v[170:173], v[56:59]
	v_mfma_f32_16x16x32_bf16 v[52:55], v[138:141], v[178:181], v[52:55]
	v_mfma_f32_16x16x32_bf16 v[48:51], v[146:149], v[178:181], v[48:51]
	v_mfma_f32_16x16x32_bf16 v[36:39], v[138:141], v[186:189], v[36:39]
	v_mfma_f32_16x16x32_bf16 v[32:35], v[146:149], v[186:189], v[32:35]
	v_mfma_f32_16x16x32_bf16 v[20:23], v[138:141], v[206:209], v[20:23]
	v_mfma_f32_16x16x32_bf16 v[16:19], v[146:149], v[206:209], v[16:19]
	v_mfma_f32_16x16x32_bf16 v[60:63], v[142:145], v[174:177], v[60:63]
	v_mfma_f32_16x16x32_bf16 v[56:59], v[150:153], v[174:177], v[56:59]
	v_mfma_f32_16x16x32_bf16 v[52:55], v[142:145], v[182:185], v[52:55]
	v_mfma_f32_16x16x32_bf16 v[48:51], v[150:153], v[182:185], v[48:51]
	v_mfma_f32_16x16x32_bf16 v[36:39], v[142:145], v[190:193], v[36:39]
	v_mfma_f32_16x16x32_bf16 v[32:35], v[150:153], v[190:193], v[32:35]
	v_mfma_f32_16x16x32_bf16 v[20:23], v[142:145], v[210:213], v[20:23]
	v_mfma_f32_16x16x32_bf16 v[16:19], v[150:153], v[210:213], v[16:19]
	v_mfma_f32_16x16x32_bf16 v[44:47], v[154:157], v[170:173], v[44:47]
	v_mfma_f32_16x16x32_bf16 v[40:43], v[162:165], v[170:173], v[40:43]
	v_mfma_f32_16x16x32_bf16 v[28:31], v[154:157], v[178:181], v[28:31]
	v_mfma_f32_16x16x32_bf16 v[24:27], v[162:165], v[178:181], v[24:27]
	v_mfma_f32_16x16x32_bf16 v[12:15], v[154:157], v[186:189], v[12:15]
	v_mfma_f32_16x16x32_bf16 v[8:11], v[162:165], v[186:189], v[8:11]
	v_mfma_f32_16x16x32_bf16 v[4:7], v[154:157], v[206:209], v[4:7]
	v_mfma_f32_16x16x32_bf16 v[0:3], v[162:165], v[206:209], v[0:3]
	v_mfma_f32_16x16x32_bf16 v[44:47], v[158:161], v[174:177], v[44:47]
	v_mfma_f32_16x16x32_bf16 v[40:43], v[166:169], v[174:177], v[40:43]
	v_mfma_f32_16x16x32_bf16 v[28:31], v[158:161], v[182:185], v[28:31]
	v_mfma_f32_16x16x32_bf16 v[24:27], v[166:169], v[182:185], v[24:27]
	v_mfma_f32_16x16x32_bf16 v[12:15], v[158:161], v[190:193], v[12:15]
	v_mfma_f32_16x16x32_bf16 v[8:11], v[166:169], v[190:193], v[8:11]
	v_mfma_f32_16x16x32_bf16 v[4:7], v[158:161], v[210:213], v[4:7]
	v_mfma_f32_16x16x32_bf16 v[0:3], v[166:169], v[210:213], v[0:3]
	s_barrier
	s_andn2_b64 vcc, exec, s[40:41]
	s_mov_b64 s[42:43], -1
	s_mov_b64 s[40:41], 0
	s_movk_i32 s44, 0x100
	s_cbranch_vccz .LBB1_395
	v_readlane_b32 s44, v255, 38
	s_and_b64 vcc, exec, s[16:17]
	v_readlane_b32 s45, v255, 39
	s_cbranch_vccz .LBB1_398
	s_barrier

.LBB1_405:
	v_and_b32_e32 v1, 48, v0
	v_lshlrev_b32_e32 v6, 6, v0
	s_movk_i32 s18, 0x3c0
	v_lshlrev_b32_e32 v0, 2, v0
	s_and_b32 s26, s16, 3
	s_lshl_b32 s24, s17, 6
	s_lshl_b32 s17, s17, 13
	v_and_or_b32 v1, v6, s18, v1
	v_and_b32_e32 v0, 32, v0
	v_lshl_add_u64 v[2:3], s[36:37], 0, v[112:113]
	v_mov_b32_e32 v131, v113
	v_bitop3_b32 v6, v1, s17, v0 bitop3:0xde
	s_lshl_b32 s17, s26, 12
	v_lshl_add_u64 v[4:5], s[36:37], 0, v[130:131]
	v_bitop3_b32 v136, v1, s17, v0 bitop3:0xde
	s_add_i32 m0, s7, 0x18000
	v_lshl_add_u64 v[0:1], v[2:3], 0, s[48:49]
	v_readlane_b32 s18, v254, 42
	v_mov_b32_e32 v135, v113
	s_waitcnt vmcnt(2)
	s_barrier
	global_load_lds_dwordx4 v[0:1], off
	v_lshl_add_u64 v[0:1], v[4:5], 0, s[48:49]
	s_add_i32 m0, s7, 0x1a000
	v_readlane_b32 s19, v254, 43
	s_add_i32 s25, s7, 0x8000
	v_mov_b32_e32 v133, v113
	global_load_lds_dwordx4 v[0:1], off
	v_lshl_add_u64 v[0:1], s[18:19], 0, v[134:135]
	s_mov_b32 m0, s25
	s_add_i32 s54, s7, 0xa000
	global_load_lds_dwordx4 v[0:1], off
	v_lshl_add_u64 v[0:1], s[18:19], 0, v[132:133]
	s_add_u32 s18, s36, 0xb0080
	s_mov_b32 m0, s54
	s_addc_u32 s19, s37, 0
	global_load_lds_dwordx4 v[0:1], off
	s_add_i32 m0, s7, 0x1c000
	v_lshl_add_u64 v[0:1], s[18:19], 0, v[112:113]
	global_load_lds_dwordx4 v[0:1], off
	v_lshl_add_u64 v[0:1], s[18:19], 0, v[130:131]
	s_add_i32 m0, s7, 0x1e000
	s_cmp_lt_u32 s16, 4
	s_cbranch_scc0 .Lgp_2
	s_setprio 1
.Lgp_2:
	global_load_lds_dwordx4 v[0:1], off
	s_waitcnt vmcnt(6)
	v_readlane_b32 s90, v254, 46
	s_cselect_b64 s[16:17], -1, 0
	s_lshl_b32 s55, s26, 6
	s_mov_b32 s56, 0
	v_add_u32_e32 v137, 0, v6
	s_mov_b32 s66, s1
	v_readlane_b32 s91, v254, 47
	s_barrier
	s_branch .LBB1_408

.LBB1_411:
	s_add_i32 s43, s42, 0x100
	s_and_b64 s[44:45], s[40:41], exec
	s_cselect_b32 s43, 0, s43
	s_cselect_b32 s45, 0, 0
	s_add_u32 s44, s50, s43
	s_addc_u32 s45, s51, s45
	s_add_u32 s43, s36, s42
	s_addc_u32 s58, s37, 0
	s_add_u32 s43, s43, 0x100
	s_addc_u32 s58, s58, 0
	s_add_i32 s81, 0, 0x10000
	s_and_b64 s[40:41], s[40:41], exec
	s_cselect_b32 s59, s67, s58
	s_cselect_b32 s58, s68, s43
	s_add_i32 s41, 0, 0x14000
	s_add_u32 s40, s22, s42
	s_addc_u32 s42, s23, 0
	s_add_u32 s62, s40, 0x520080
	s_addc_u32 s63, s42, 0
	s_add_i32 s80, s81, s5
	s_add_i32 m0, s7, 0xc000
	s_add_i32 s83, s7, 0xe000
	s_add_i32 s77, s80, 0x2000
	s_add_u32 s60, s58, 0xb0000
	v_add_u32_e32 v150, s81, v136
	v_add_u32_e32 v166, s41, v136
	s_addc_u32 s61, s59, 0
	s_add_i32 s79, s41, s5
	ds_read_b128 v[138:141], v150
	ds_read_b128 v[142:145], v150 offset:1024
	ds_read_b128 v[146:149], v150 offset:2048
	ds_read_b128 v[150:153], v150 offset:3072
	ds_read_b128 v[154:157], v166
	ds_read_b128 v[158:161], v166 offset:1024
	ds_read_b128 v[162:165], v166 offset:2048
	ds_read_b128 v[166:169], v166 offset:3072
	s_add_i32 s78, s79, 0x2000
	s_add_i32 s76, 0, 0x18000
	s_add_i32 s75, 0, 0x1c000
	s_add_u32 s42, s44, 0x10000
	s_addc_u32 s43, s45, 0
	s_add_i32 s74, s76, s5
	s_add_i32 s72, s74, 0x2000
	s_add_u32 s40, s58, 0xb0080
	s_addc_u32 s41, s59, 0
	s_add_i32 s82, s75, s5
	s_add_i32 s81, s82, 0x2000
	v_lshl_add_u64 v[198:199], s[62:63], 0, v[134:135]
	ds_read_b128 v[170:173], v137
	ds_read_b128 v[174:177], v137 offset:1024
	ds_read_b128 v[178:181], v137 offset:2048
	ds_read_b128 v[182:185], v137 offset:3072
	ds_read_b128 v[186:189], v137 offset:4096
	ds_read_b128 v[190:193], v137 offset:5120
	ds_read_b128 v[206:209], v137 offset:6144
	ds_read_b128 v[210:213], v137 offset:7168
	global_load_lds_dwordx4 v[198:199], off
	v_lshl_add_u64 v[198:199], s[62:63], 0, v[132:133]
	s_mov_b32 m0, s83
	s_nop 0
	global_load_lds_dwordx4 v[198:199], off
	s_waitcnt vmcnt(8)
	s_waitcnt lgkmcnt(0)
	s_barrier
	s_waitcnt lgkmcnt(0)
	v_mfma_f32_16x16x32_bf16 v[126:129], v[138:141], v[170:173], v[126:129]
	v_mfma_f32_16x16x32_bf16 v[122:125], v[146:149], v[170:173], v[122:125]
	v_mfma_f32_16x16x32_bf16 v[118:121], v[138:141], v[178:181], v[118:121]
	v_mfma_f32_16x16x32_bf16 v[114:117], v[146:149], v[178:181], v[114:117]
	v_mfma_f32_16x16x32_bf16 v[100:103], v[138:141], v[186:189], v[100:103]
	v_mfma_f32_16x16x32_bf16 v[96:99], v[146:149], v[186:189], v[96:99]
	v_mfma_f32_16x16x32_bf16 v[84:87], v[138:141], v[206:209], v[84:87]
	v_mfma_f32_16x16x32_bf16 v[80:83], v[146:149], v[206:209], v[80:83]
	v_mfma_f32_16x16x32_bf16 v[126:129], v[142:145], v[174:177], v[126:129]
	v_mfma_f32_16x16x32_bf16 v[122:125], v[150:153], v[174:177], v[122:125]
	v_mfma_f32_16x16x32_bf16 v[118:121], v[142:145], v[182:185], v[118:121]
	v_mfma_f32_16x16x32_bf16 v[114:117], v[150:153], v[182:185], v[114:117]
	v_mfma_f32_16x16x32_bf16 v[100:103], v[142:145], v[190:193], v[100:103]
	v_mfma_f32_16x16x32_bf16 v[96:99], v[150:153], v[190:193], v[96:99]
	v_mfma_f32_16x16x32_bf16 v[84:87], v[142:145], v[210:213], v[84:87]
	v_mfma_f32_16x16x32_bf16 v[80:83], v[150:153], v[210:213], v[80:83]
	v_mfma_f32_16x16x32_bf16 v[108:111], v[154:157], v[170:173], v[108:111]
	v_mfma_f32_16x16x32_bf16 v[104:107], v[162:165], v[170:173], v[104:107]
	v_mfma_f32_16x16x32_bf16 v[92:95], v[154:157], v[178:181], v[92:95]
	v_mfma_f32_16x16x32_bf16 v[88:91], v[162:165], v[178:181], v[88:91]
	v_mfma_f32_16x16x32_bf16 v[76:79], v[154:157], v[186:189], v[76:79]
	v_mfma_f32_16x16x32_bf16 v[72:75], v[162:165], v[186:189], v[72:75]
	v_mfma_f32_16x16x32_bf16 v[68:71], v[154:157], v[206:209], v[68:71]
	v_mfma_f32_16x16x32_bf16 v[64:67], v[162:165], v[206:209], v[64:67]
	v_mfma_f32_16x16x32_bf16 v[108:111], v[158:161], v[174:177], v[108:111]
	v_mfma_f32_16x16x32_bf16 v[104:107], v[166:169], v[174:177], v[104:107]
	v_mfma_f32_16x16x32_bf16 v[92:95], v[158:161], v[182:185], v[92:95]
	v_mfma_f32_16x16x32_bf16 v[88:91], v[166:169], v[182:185], v[88:91]
	v_mfma_f32_16x16x32_bf16 v[76:79], v[158:161], v[190:193], v[76:79]
	v_mfma_f32_16x16x32_bf16 v[72:75], v[166:169], v[190:193], v[72:75]
	v_mfma_f32_16x16x32_bf16 v[68:71], v[158:161], v[210:213], v[68:71]
	v_mfma_f32_16x16x32_bf16 v[64:67], v[166:169], v[210:213], v[64:67]
	s_barrier
	s_mov_b32 m0, s80
	v_lshl_add_u64 v[198:199], s[58:59], 0, v[112:113]
	ds_read_b128 v[170:173], v137 offset:16384
	ds_read_b128 v[174:177], v137 offset:17408
	ds_read_b128 v[178:181], v137 offset:18432
	ds_read_b128 v[182:185], v137 offset:19456
	ds_read_b128 v[186:189], v137 offset:20480
	ds_read_b128 v[190:193], v137 offset:21504
	ds_read_b128 v[206:209], v137 offset:22528
	ds_read_b128 v[210:213], v137 offset:23552
	global_load_lds_dwordx4 v[198:199], off
	v_lshl_add_u64 v[200:201], s[58:59], 0, v[130:131]
	s_mov_b32 m0, s77
	v_lshl_add_u64 v[234:235], s[60:61], 0, v[112:113]
	global_load_lds_dwordx4 v[200:201], off
	s_mov_b32 m0, s79
	v_lshl_add_u64 v[236:237], s[44:45], 0, v[132:133]
	global_load_lds_dwordx4 v[234:235], off
	v_lshl_add_u64 v[234:235], s[60:61], 0, v[130:131]
	s_mov_b32 m0, s78
	s_nop 0
	global_load_lds_dwordx4 v[234:235], off
	v_lshl_add_u64 v[234:235], s[44:45], 0, v[134:135]
	s_mov_b32 m0, s7
	s_nop 0
	global_load_lds_dwordx4 v[234:235], off
	s_mov_b32 m0, s9
	s_nop 0
	global_load_lds_dwordx4 v[236:237], off
	s_waitcnt vmcnt(8)
	s_waitcnt lgkmcnt(0)
	s_barrier
	s_waitcnt lgkmcnt(0)
	v_mfma_f32_16x16x32_bf16 v[60:63], v[138:141], v[170:173], v[60:63]
	v_mfma_f32_16x16x32_bf16 v[56:59], v[146:149], v[170:173], v[56:59]
	v_mfma_f32_16x16x32_bf16 v[52:55], v[138:141], v[178:181], v[52:55]
	v_mfma_f32_16x16x32_bf16 v[48:51], v[146:149], v[178:181], v[48:51]
	v_mfma_f32_16x16x32_bf16 v[36:39], v[138:141], v[186:189], v[36:39]
	v_mfma_f32_16x16x32_bf16 v[32:35], v[146:149], v[186:189], v[32:35]
	v_mfma_f32_16x16x32_bf16 v[20:23], v[138:141], v[206:209], v[20:23]
	v_mfma_f32_16x16x32_bf16 v[16:19], v[146:149], v[206:209], v[16:19]
	v_mfma_f32_16x16x32_bf16 v[60:63], v[142:145], v[174:177], v[60:63]
	v_mfma_f32_16x16x32_bf16 v[56:59], v[150:153], v[174:177], v[56:59]
	v_mfma_f32_16x16x32_bf16 v[52:55], v[142:145], v[182:185], v[52:55]
	v_mfma_f32_16x16x32_bf16 v[48:51], v[150:153], v[182:185], v[48:51]
	v_mfma_f32_16x16x32_bf16 v[36:39], v[142:145], v[190:193], v[36:39]
	v_mfma_f32_16x16x32_bf16 v[32:35], v[150:153], v[190:193], v[32:35]
	v_mfma_f32_16x16x32_bf16 v[20:23], v[142:145], v[210:213], v[20:23]
	v_mfma_f32_16x16x32_bf16 v[16:19], v[150:153], v[210:213], v[16:19]
	v_mfma_f32_16x16x32_bf16 v[44:47], v[154:157], v[170:173], v[44:47]
	v_mfma_f32_16x16x32_bf16 v[40:43], v[162:165], v[170:173], v[40:43]
	v_mfma_f32_16x16x32_bf16 v[28:31], v[154:157], v[178:181], v[28:31]
	v_mfma_f32_16x16x32_bf16 v[24:27], v[162:165], v[178:181], v[24:27]
	v_mfma_f32_16x16x32_bf16 v[12:15], v[154:157], v[186:189], v[12:15]
	v_mfma_f32_16x16x32_bf16 v[8:11], v[162:165], v[186:189], v[8:11]
	v_mfma_f32_16x16x32_bf16 v[4:7], v[154:157], v[206:209], v[4:7]
	v_mfma_f32_16x16x32_bf16 v[0:3], v[162:165], v[206:209], v[0:3]
	v_mfma_f32_16x16x32_bf16 v[44:47], v[158:161], v[174:177], v[44:47]
	v_mfma_f32_16x16x32_bf16 v[40:43], v[166:169], v[174:177], v[40:43]
	v_mfma_f32_16x16x32_bf16 v[28:31], v[158:161], v[182:185], v[28:31]
	v_mfma_f32_16x16x32_bf16 v[24:27], v[166:169], v[182:185], v[24:27]
	v_mfma_f32_16x16x32_bf16 v[12:15], v[158:161], v[190:193], v[12:15]
	v_mfma_f32_16x16x32_bf16 v[8:11], v[166:169], v[190:193], v[8:11]
	v_mfma_f32_16x16x32_bf16 v[4:7], v[158:161], v[210:213], v[4:7]
	v_mfma_f32_16x16x32_bf16 v[0:3], v[166:169], v[210:213], v[0:3]
	s_barrier
	v_add_u32_e32 v150, s76, v136
	v_add_u32_e32 v166, s75, v136
	ds_read_b128 v[138:141], v150
	ds_read_b128 v[142:145], v150 offset:1024
	ds_read_b128 v[146:149], v150 offset:2048
	ds_read_b128 v[150:153], v150 offset:3072
	ds_read_b128 v[154:157], v166
	ds_read_b128 v[158:161], v166 offset:1024
	ds_read_b128 v[162:165], v166 offset:2048
	ds_read_b128 v[166:169], v166 offset:3072
	s_mov_b32 m0, s10
	v_lshl_add_u64 v[238:239], s[42:43], 0, v[134:135]
	ds_read_b128 v[170:173], v137 offset:32768
	ds_read_b128 v[174:177], v137 offset:33792
	ds_read_b128 v[178:181], v137 offset:34816
	ds_read_b128 v[182:185], v137 offset:35840
	ds_read_b128 v[186:189], v137 offset:36864
	ds_read_b128 v[190:193], v137 offset:37888
	ds_read_b128 v[206:209], v137 offset:38912
	ds_read_b128 v[210:213], v137 offset:39936
	global_load_lds_dwordx4 v[238:239], off
	v_lshl_add_u64 v[238:239], s[42:43], 0, v[132:133]
	s_mov_b32 m0, s11
	s_nop 0
	global_load_lds_dwordx4 v[238:239], off
	s_waitcnt vmcnt(8)
	s_waitcnt lgkmcnt(0)
	s_barrier
	s_waitcnt lgkmcnt(0)
	v_mfma_f32_16x16x32_bf16 v[126:129], v[138:141], v[170:173], v[126:129]
	v_mfma_f32_16x16x32_bf16 v[122:125], v[146:149], v[170:173], v[122:125]
	v_mfma_f32_16x16x32_bf16 v[118:121], v[138:141], v[178:181], v[118:121]
	v_mfma_f32_16x16x32_bf16 v[114:117], v[146:149], v[178:181], v[114:117]
	v_mfma_f32_16x16x32_bf16 v[100:103], v[138:141], v[186:189], v[100:103]
	v_mfma_f32_16x16x32_bf16 v[96:99], v[146:149], v[186:189], v[96:99]
	v_mfma_f32_16x16x32_bf16 v[84:87], v[138:141], v[206:209], v[84:87]
	v_mfma_f32_16x16x32_bf16 v[80:83], v[146:149], v[206:209], v[80:83]
	v_mfma_f32_16x16x32_bf16 v[126:129], v[142:145], v[174:177], v[126:129]
	v_mfma_f32_16x16x32_bf16 v[122:125], v[150:153], v[174:177], v[122:125]
	v_mfma_f32_16x16x32_bf16 v[118:121], v[142:145], v[182:185], v[118:121]
	v_mfma_f32_16x16x32_bf16 v[114:117], v[150:153], v[182:185], v[114:117]
	v_mfma_f32_16x16x32_bf16 v[100:103], v[142:145], v[190:193], v[100:103]
	v_mfma_f32_16x16x32_bf16 v[96:99], v[150:153], v[190:193], v[96:99]
	v_mfma_f32_16x16x32_bf16 v[84:87], v[142:145], v[210:213], v[84:87]
	v_mfma_f32_16x16x32_bf16 v[80:83], v[150:153], v[210:213], v[80:83]
	v_mfma_f32_16x16x32_bf16 v[108:111], v[154:157], v[170:173], v[108:111]
	v_mfma_f32_16x16x32_bf16 v[104:107], v[162:165], v[170:173], v[104:107]
	v_mfma_f32_16x16x32_bf16 v[92:95], v[154:157], v[178:181], v[92:95]
	v_mfma_f32_16x16x32_bf16 v[88:91], v[162:165], v[178:181], v[88:91]
	v_mfma_f32_16x16x32_bf16 v[76:79], v[154:157], v[186:189], v[76:79]
	v_mfma_f32_16x16x32_bf16 v[72:75], v[162:165], v[186:189], v[72:75]
	v_mfma_f32_16x16x32_bf16 v[68:71], v[154:157], v[206:209], v[68:71]
	v_mfma_f32_16x16x32_bf16 v[64:67], v[162:165], v[206:209], v[64:67]
	v_mfma_f32_16x16x32_bf16 v[108:111], v[158:161], v[174:177], v[108:111]
	v_mfma_f32_16x16x32_bf16 v[104:107], v[166:169], v[174:177], v[104:107]
	v_mfma_f32_16x16x32_bf16 v[92:95], v[158:161], v[182:185], v[92:95]
	v_mfma_f32_16x16x32_bf16 v[88:91], v[166:169], v[182:185], v[88:91]
	v_mfma_f32_16x16x32_bf16 v[76:79], v[158:161], v[190:193], v[76:79]
	v_mfma_f32_16x16x32_bf16 v[72:75], v[166:169], v[190:193], v[72:75]
	v_mfma_f32_16x16x32_bf16 v[68:71], v[158:161], v[210:213], v[68:71]
	v_mfma_f32_16x16x32_bf16 v[64:67], v[166:169], v[210:213], v[64:67]
	s_barrier
	s_mov_b32 m0, s74
	v_lshl_add_u64 v[198:199], v[198:199], 0, s[48:49]
	ds_read_b128 v[170:173], v137 offset:49152
	ds_read_b128 v[174:177], v137 offset:50176
	ds_read_b128 v[178:181], v137 offset:51200
	ds_read_b128 v[182:185], v137 offset:52224
	ds_read_b128 v[186:189], v137 offset:53248
	ds_read_b128 v[190:193], v137 offset:54272
	ds_read_b128 v[206:209], v137 offset:55296
	ds_read_b128 v[210:213], v137 offset:56320
	global_load_lds_dwordx4 v[198:199], off
	v_lshl_add_u64 v[198:199], v[200:201], 0, s[48:49]
	s_mov_b32 m0, s72
	s_nop 0
	global_load_lds_dwordx4 v[198:199], off
	v_lshl_add_u64 v[198:199], s[40:41], 0, v[112:113]
	s_mov_b32 m0, s82
	s_nop 0
	global_load_lds_dwordx4 v[198:199], off
	v_lshl_add_u64 v[198:199], s[40:41], 0, v[130:131]
	s_mov_b32 m0, s81
	s_nop 0
	global_load_lds_dwordx4 v[198:199], off
	v_lshl_add_u64 v[198:199], v[234:235], 0, s[48:49]
	s_mov_b32 m0, s25
	s_nop 0
	global_load_lds_dwordx4 v[198:199], off
	v_lshl_add_u64 v[198:199], v[236:237], 0, s[48:49]
	s_mov_b32 m0, s54
	s_nop 0
	global_load_lds_dwordx4 v[198:199], off
	s_waitcnt vmcnt(8)
	s_waitcnt lgkmcnt(0)
	s_barrier
	s_waitcnt lgkmcnt(0)
	v_mfma_f32_16x16x32_bf16 v[60:63], v[138:141], v[170:173], v[60:63]
	v_mfma_f32_16x16x32_bf16 v[56:59], v[146:149], v[170:173], v[56:59]
	v_mfma_f32_16x16x32_bf16 v[52:55], v[138:141], v[178:181], v[52:55]
	v_mfma_f32_16x16x32_bf16 v[48:51], v[146:149], v[178:181], v[48:51]
	v_mfma_f32_16x16x32_bf16 v[36:39], v[138:141], v[186:189], v[36:39]
	v_mfma_f32_16x16x32_bf16 v[32:35], v[146:149], v[186:189], v[32:35]
	v_mfma_f32_16x16x32_bf16 v[20:23], v[138:141], v[206:209], v[20:23]
	v_mfma_f32_16x16x32_bf16 v[16:19], v[146:149], v[206:209], v[16:19]
	v_mfma_f32_16x16x32_bf16 v[60:63], v[142:145], v[174:177], v[60:63]
	v_mfma_f32_16x16x32_bf16 v[56:59], v[150:153], v[174:177], v[56:59]
	v_mfma_f32_16x16x32_bf16 v[52:55], v[142:145], v[182:185], v[52:55]
	v_mfma_f32_16x16x32_bf16 v[48:51], v[150:153], v[182:185], v[48:51]
	v_mfma_f32_16x16x32_bf16 v[36:39], v[142:145], v[190:193], v[36:39]
	v_mfma_f32_16x16x32_bf16 v[32:35], v[150:153], v[190:193], v[32:35]
	v_mfma_f32_16x16x32_bf16 v[20:23], v[142:145], v[210:213], v[20:23]
	v_mfma_f32_16x16x32_bf16 v[16:19], v[150:153], v[210:213], v[16:19]
	v_mfma_f32_16x16x32_bf16 v[44:47], v[154:157], v[170:173], v[44:47]
	v_mfma_f32_16x16x32_bf16 v[40:43], v[162:165], v[170:173], v[40:43]
	v_mfma_f32_16x16x32_bf16 v[28:31], v[154:157], v[178:181], v[28:31]
	v_mfma_f32_16x16x32_bf16 v[24:27], v[162:165], v[178:181], v[24:27]
	v_mfma_f32_16x16x32_bf16 v[12:15], v[154:157], v[186:189], v[12:15]
	v_mfma_f32_16x16x32_bf16 v[8:11], v[162:165], v[186:189], v[8:11]
	v_mfma_f32_16x16x32_bf16 v[4:7], v[154:157], v[206:209], v[4:7]
	v_mfma_f32_16x16x32_bf16 v[0:3], v[162:165], v[206:209], v[0:3]
	v_mfma_f32_16x16x32_bf16 v[44:47], v[158:161], v[174:177], v[44:47]
	v_mfma_f32_16x16x32_bf16 v[40:43], v[166:169], v[174:177], v[40:43]
	v_mfma_f32_16x16x32_bf16 v[28:31], v[158:161], v[182:185], v[28:31]
	v_mfma_f32_16x16x32_bf16 v[24:27], v[166:169], v[182:185], v[24:27]
	v_mfma_f32_16x16x32_bf16 v[12:15], v[158:161], v[190:193], v[12:15]
	v_mfma_f32_16x16x32_bf16 v[8:11], v[166:169], v[190:193], v[8:11]
	v_mfma_f32_16x16x32_bf16 v[4:7], v[158:161], v[210:213], v[4:7]
	v_mfma_f32_16x16x32_bf16 v[0:3], v[166:169], v[210:213], v[0:3]
	s_barrier
	s_andn2_b64 vcc, exec, s[38:39]
	s_mov_b64 s[40:41], -1
	s_mov_b64 s[38:39], 0
	s_movk_i32 s42, 0x100
	s_cbranch_vccz .LBB1_411
	s_and_b64 vcc, exec, s[16:17]
	s_cbranch_vccz .LBB1_414
	s_barrier

.LBB1_418:
	v_readlane_b32 s1, v255, 43
	s_add_i32 s1, s1, 4
	s_cmp_ge_i32 s1, s77
	s_cbranch_scc1 .LBB1_468
	s_setprio 0
	s_waitcnt vmcnt(0)
	s_waitcnt vmcnt(0)
	s_barrier
	s_mov_b64 s[2:3], exec
	v_readlane_b32 s6, v255, 20
	v_readlane_b32 s7, v255, 21
	s_and_b64 s[6:7], s[2:3], s[6:7]
	s_mov_b64 exec, s[6:7]
	s_cbranch_execz .LBB1_467
	v_readlane_b32 s5, v255, 18
	s_waitcnt vmcnt(0) expcnt(0) lgkmcnt(0)
	buffer_inv sc1
	s_nop 0
	v_mov_b32_e32 v0, s5
	ds_read_b32 v2, v0
	v_readlane_b32 s5, v255, 19
	s_waitcnt lgkmcnt(0)
	v_cmp_ne_u32_e32 vcc, 0, v2
	v_mov_b32_e32 v0, s5
	ds_read_b32 v0, v0
	s_cbranch_vccnz .LBB1_435
	v_readlane_b32 s10, v253, 8
	v_readlane_b32 s11, v253, 9
	s_load_dwordx2 s[6:7], s[10:11], 0x4
	s_waitcnt lgkmcnt(0)
	s_mul_i32 s5, s6, s33
	s_mul_i32 s5, s5, s7
	s_mov_b32 s6, 1
	s_branch .LBB1_423

.LBB1_553:
	v_readlane_b32 s1, v255, 43
	s_add_i32 s1, s1, 5
	s_cmp_ge_i32 s1, s77
	s_cbranch_scc1 .LBB1_603
	s_setprio 0
	s_waitcnt vmcnt(0)
	s_waitcnt vmcnt(0)
	s_barrier
	s_mov_b64 s[2:3], exec
	v_readlane_b32 s6, v255, 20
	v_readlane_b32 s7, v255, 21
	s_and_b64 s[6:7], s[2:3], s[6:7]
	s_mov_b64 exec, s[6:7]
	s_cbranch_execz .LBB1_602
	v_readlane_b32 s5, v255, 18
	s_waitcnt vmcnt(0) expcnt(0) lgkmcnt(0)
	buffer_inv sc1
	s_nop 0
	v_mov_b32_e32 v0, s5
	ds_read_b32 v2, v0
	v_readlane_b32 s5, v255, 19
	s_waitcnt lgkmcnt(0)
	v_cmp_ne_u32_e32 vcc, 0, v2
	v_mov_b32_e32 v0, s5
	ds_read_b32 v0, v0
	s_cbranch_vccnz .LBB1_570
	v_readlane_b32 s10, v253, 8
	v_readlane_b32 s11, v253, 9
	s_load_dwordx2 s[6:7], s[10:11], 0x4
	s_waitcnt lgkmcnt(0)
	s_mul_i32 s5, s6, s33
	s_mul_i32 s5, s5, s7
	s_mov_b32 s6, 1
	s_branch .LBB1_558

.LBB1_611:
	v_and_b32_e32 v15, 48, v12
	v_lshlrev_b32_e32 v16, 6, v12
	s_movk_i32 s3, 0x3c0
	v_lshlrev_b32_e32 v12, 2, v12
	s_and_b32 s6, s1, 3
	s_lshl_b32 s63, s2, 6
	s_lshl_b32 s2, s2, 13
	v_and_or_b32 v15, v16, s3, v15
	v_and_b32_e32 v12, 32, v12
	s_add_i32 m0, s59, 0x18000
	v_lshl_add_u64 v[4:5], v[4:5], 0, s[48:49]
	v_bitop3_b32 v16, v15, s2, v12 bitop3:0xde
	s_lshl_b32 s2, s6, 12
	s_waitcnt vmcnt(2)
	s_barrier
	global_load_lds_dwordx4 v[4:5], off
	v_lshl_add_u64 v[2:3], v[2:3], 0, s[48:49]
	s_add_i32 m0, s59, 0x1a000
	s_add_i32 s86, s59, 0x8000
	s_add_i32 s87, s59, 0xa000
	v_bitop3_b32 v154, v15, s2, v12 bitop3:0xde
	global_load_lds_dwordx4 v[2:3], off
	v_lshl_add_u64 v[0:1], v[0:1], 0, s[48:49]
	s_mov_b32 m0, s86
	s_add_u32 s2, s18, 0x20080
	global_load_lds_dwordx4 v[0:1], off
	v_lshl_add_u64 v[0:1], v[6:7], 0, s[48:49]
	s_mov_b32 m0, s87
	s_addc_u32 s3, s19, 0
	global_load_lds_dwordx4 v[0:1], off
	s_add_i32 m0, s59, 0x1c000
	v_lshl_add_u64 v[0:1], s[2:3], 0, v[134:135]
	global_load_lds_dwordx4 v[0:1], off
	v_lshl_add_u64 v[0:1], s[2:3], 0, v[138:139]
	s_add_i32 m0, s59, 0x1e000
	s_lshl_b32 s92, s6, 6
	global_load_lds_dwordx4 v[0:1], off
	v_lshlrev_b32_e32 v0, 15, v8
	v_and_b32_e32 v0, 0xffff0000, v0
	v_lshl_add_u32 v0, v9, 12, v0
	v_and_b32_e32 v1, 1, v8
	v_lshl_or_b32 v0, v1, 6, v0
	v_lshl_add_u32 v140, v10, 1, v0
	v_lshlrev_b32_e32 v0, 15, v11
	v_and_b32_e32 v0, 0xffff0000, v0
	s_waitcnt vmcnt(6)
	v_lshl_add_u32 v0, v13, 12, v0
	v_and_b32_e32 v1, 1, v11
	s_cmp_lt_u32 s1, 4
	s_cbranch_scc0 .Lgp_3
	s_setprio 1
.Lgp_3:
	v_lshl_or_b32 v0, v1, 6, v0
	s_sext_i32_i8 s5, s26
	s_cselect_b64 s[42:43], -1, 0
	v_mov_b32_e32 v141, v113
	v_lshl_add_u32 v142, v14, 1, v0
	v_mov_b32_e32 v143, v113
	s_mov_b32 s93, 0
	v_add_u32_e32 v155, 0, v16
	s_movk_i32 s25, 0x120
	s_barrier
	s_branch .LBB1_614

.LBB1_621:
	s_add_u32 s5, s82, s84
	s_addc_u32 s6, s83, s85
	s_add_u32 s5, s5, 0x100
	s_addc_u32 s6, s6, 0
	s_add_u32 s7, s56, s84
	s_addc_u32 s9, s57, s85
	s_add_i32 s10, 0, 0x10000
	s_cmpk_eq_i32 s84, 0xf00
	s_cselect_b32 s19, s3, s6
	s_cselect_b32 s18, s24, s5
	v_add_u32_e32 v112, s10, v154
	s_cselect_b32 s17, s1, s9
	s_cselect_b32 s16, s45, s7
	s_add_i32 s5, 0, 0x14000
	ds_read_b128 v[148:151], v112
	ds_read_b128 v[156:159], v112 offset:1024
	ds_read_b128 v[160:163], v112 offset:2048
	ds_read_b128 v[164:167], v112 offset:3072
	v_add_u32_e32 v112, s5, v154
	ds_read_b128 v[168:171], v112
	ds_read_b128 v[172:175], v112 offset:1024
	ds_read_b128 v[176:179], v112 offset:2048
	ds_read_b128 v[180:183], v112 offset:3072
	v_lshl_add_u64 v[114:115], v[144:145], 0, s[84:85]
	s_add_i32 m0, s59, 0xc000
	ds_read_b128 v[184:187], v155
	ds_read_b128 v[188:191], v155 offset:1024
	ds_read_b128 v[198:201], v155 offset:2048
	ds_read_b128 v[206:209], v155 offset:3072
	ds_read_b128 v[210:213], v155 offset:4096
	ds_read_b128 v[234:237], v155 offset:5120
	ds_read_b128 v[238:241], v155 offset:6144
	ds_read_b128 v[242:245], v155 offset:7168
	global_load_lds_dwordx4 v[114:115], off
	v_lshl_add_u64 v[114:115], v[146:147], 0, s[84:85]
	s_add_i32 m0, s59, 0xe000
	s_nop 0
	global_load_lds_dwordx4 v[114:115], off
	s_waitcnt vmcnt(8)
	s_waitcnt lgkmcnt(0)
	s_barrier
	s_waitcnt lgkmcnt(0)
	v_mfma_f32_16x16x32_bf16 v[128:131], v[148:151], v[184:187], v[128:131]
	v_mfma_f32_16x16x32_bf16 v[124:127], v[160:163], v[184:187], v[124:127]
	v_mfma_f32_16x16x32_bf16 v[108:111], v[148:151], v[198:201], v[108:111]
	v_mfma_f32_16x16x32_bf16 v[104:107], v[160:163], v[198:201], v[104:107]
	v_mfma_f32_16x16x32_bf16 v[92:95], v[148:151], v[210:213], v[92:95]
	v_mfma_f32_16x16x32_bf16 v[88:91], v[160:163], v[210:213], v[88:91]
	v_mfma_f32_16x16x32_bf16 v[76:79], v[148:151], v[238:241], v[76:79]
	v_mfma_f32_16x16x32_bf16 v[72:75], v[160:163], v[238:241], v[72:75]
	v_mfma_f32_16x16x32_bf16 v[128:131], v[156:159], v[188:191], v[128:131]
	v_mfma_f32_16x16x32_bf16 v[124:127], v[164:167], v[188:191], v[124:127]
	v_mfma_f32_16x16x32_bf16 v[108:111], v[156:159], v[206:209], v[108:111]
	v_mfma_f32_16x16x32_bf16 v[104:107], v[164:167], v[206:209], v[104:107]
	v_mfma_f32_16x16x32_bf16 v[92:95], v[156:159], v[234:237], v[92:95]
	v_mfma_f32_16x16x32_bf16 v[88:91], v[164:167], v[234:237], v[88:91]
	v_mfma_f32_16x16x32_bf16 v[76:79], v[156:159], v[242:245], v[76:79]
	v_mfma_f32_16x16x32_bf16 v[72:75], v[164:167], v[242:245], v[72:75]
	v_mfma_f32_16x16x32_bf16 v[120:123], v[168:171], v[184:187], v[120:123]
	v_mfma_f32_16x16x32_bf16 v[114:117], v[176:179], v[184:187], v[116:119]
	v_mfma_f32_16x16x32_bf16 v[100:103], v[168:171], v[198:201], v[100:103]
	v_mfma_f32_16x16x32_bf16 v[96:99], v[176:179], v[198:201], v[96:99]
	v_mfma_f32_16x16x32_bf16 v[84:87], v[168:171], v[210:213], v[84:87]
	v_mfma_f32_16x16x32_bf16 v[80:83], v[176:179], v[210:213], v[80:83]
	v_mfma_f32_16x16x32_bf16 v[68:71], v[168:171], v[238:241], v[68:71]
	v_mfma_f32_16x16x32_bf16 v[64:67], v[176:179], v[238:241], v[64:67]
	v_mfma_f32_16x16x32_bf16 v[120:123], v[172:175], v[188:191], v[120:123]
	v_mfma_f32_16x16x32_bf16 v[114:117], v[180:183], v[188:191], v[114:117]
	v_mfma_f32_16x16x32_bf16 v[100:103], v[172:175], v[206:209], v[100:103]
	v_mfma_f32_16x16x32_bf16 v[96:99], v[180:183], v[206:209], v[96:99]
	v_mfma_f32_16x16x32_bf16 v[84:87], v[172:175], v[234:237], v[84:87]
	v_mfma_f32_16x16x32_bf16 v[80:83], v[180:183], v[234:237], v[80:83]
	v_mfma_f32_16x16x32_bf16 v[68:71], v[172:175], v[242:245], v[68:71]
	v_mfma_f32_16x16x32_bf16 v[64:67], v[180:183], v[242:245], v[64:67]
	s_barrier
	s_add_i32 s6, s10, s58
	v_lshl_add_u64 v[152:153], s[16:17], 0, v[134:135]
	s_mov_b32 m0, s6
	ds_read_b128 v[184:187], v155 offset:16384
	ds_read_b128 v[188:191], v155 offset:17408
	ds_read_b128 v[198:201], v155 offset:18432
	ds_read_b128 v[206:209], v155 offset:19456
	ds_read_b128 v[210:213], v155 offset:20480
	ds_read_b128 v[234:237], v155 offset:21504
	ds_read_b128 v[238:241], v155 offset:22528
	ds_read_b128 v[242:245], v155 offset:23552
	global_load_lds_dwordx4 v[152:153], off
	s_add_i32 m0, s6, 0x2000
	s_add_u32 s6, s16, 0x20000
	v_lshl_add_u64 v[192:193], s[16:17], 0, v[138:139]
	s_addc_u32 s7, s17, 0
	s_add_i32 s5, s5, s58
	global_load_lds_dwordx4 v[192:193], off
	v_lshl_add_u64 v[118:119], s[6:7], 0, v[134:135]
	s_mov_b32 m0, s5
	v_lshl_add_u64 v[246:247], s[18:19], 0, v[132:133]
	global_load_lds_dwordx4 v[118:119], off
	v_lshl_add_u64 v[118:119], s[6:7], 0, v[138:139]
	s_add_i32 m0, s5, 0x2000
	v_lshl_add_u64 v[248:249], s[18:19], 0, v[136:137]
	global_load_lds_dwordx4 v[118:119], off
	s_mov_b32 m0, s59
	s_nop 0
	global_load_lds_dwordx4 v[246:247], off
	s_mov_b32 m0, s60
	s_nop 0
	global_load_lds_dwordx4 v[248:249], off
	s_waitcnt vmcnt(8)
	s_waitcnt lgkmcnt(0)
	s_barrier
	s_waitcnt lgkmcnt(0)
	v_mfma_f32_16x16x32_bf16 v[60:63], v[148:151], v[184:187], v[60:63]
	v_mfma_f32_16x16x32_bf16 v[56:59], v[160:163], v[184:187], v[56:59]
	v_mfma_f32_16x16x32_bf16 v[44:47], v[148:151], v[198:201], v[44:47]
	v_mfma_f32_16x16x32_bf16 v[40:43], v[160:163], v[198:201], v[40:43]
	v_mfma_f32_16x16x32_bf16 v[28:31], v[148:151], v[210:213], v[28:31]
	v_mfma_f32_16x16x32_bf16 v[24:27], v[160:163], v[210:213], v[24:27]
	v_mfma_f32_16x16x32_bf16 v[12:15], v[148:151], v[238:241], v[12:15]
	v_mfma_f32_16x16x32_bf16 v[8:11], v[160:163], v[238:241], v[8:11]
	v_mfma_f32_16x16x32_bf16 v[60:63], v[156:159], v[188:191], v[60:63]
	v_mfma_f32_16x16x32_bf16 v[56:59], v[164:167], v[188:191], v[56:59]
	v_mfma_f32_16x16x32_bf16 v[44:47], v[156:159], v[206:209], v[44:47]
	v_mfma_f32_16x16x32_bf16 v[40:43], v[164:167], v[206:209], v[40:43]
	v_mfma_f32_16x16x32_bf16 v[28:31], v[156:159], v[234:237], v[28:31]
	v_mfma_f32_16x16x32_bf16 v[24:27], v[164:167], v[234:237], v[24:27]
	v_mfma_f32_16x16x32_bf16 v[12:15], v[156:159], v[242:245], v[12:15]
	v_mfma_f32_16x16x32_bf16 v[8:11], v[164:167], v[242:245], v[8:11]
	v_mfma_f32_16x16x32_bf16 v[52:55], v[168:171], v[184:187], v[52:55]
	v_mfma_f32_16x16x32_bf16 v[48:51], v[176:179], v[184:187], v[48:51]
	v_mfma_f32_16x16x32_bf16 v[36:39], v[168:171], v[198:201], v[36:39]
	v_mfma_f32_16x16x32_bf16 v[32:35], v[176:179], v[198:201], v[32:35]
	v_mfma_f32_16x16x32_bf16 v[20:23], v[168:171], v[210:213], v[20:23]
	v_mfma_f32_16x16x32_bf16 v[16:19], v[176:179], v[210:213], v[16:19]
	v_mfma_f32_16x16x32_bf16 v[4:7], v[168:171], v[238:241], v[4:7]
	v_mfma_f32_16x16x32_bf16 v[0:3], v[176:179], v[238:241], v[0:3]
	v_mfma_f32_16x16x32_bf16 v[52:55], v[172:175], v[188:191], v[52:55]
	v_mfma_f32_16x16x32_bf16 v[48:51], v[180:183], v[188:191], v[48:51]
	v_mfma_f32_16x16x32_bf16 v[36:39], v[172:175], v[206:209], v[36:39]
	v_mfma_f32_16x16x32_bf16 v[32:35], v[180:183], v[206:209], v[32:35]
	v_mfma_f32_16x16x32_bf16 v[20:23], v[172:175], v[234:237], v[20:23]
	v_mfma_f32_16x16x32_bf16 v[16:19], v[180:183], v[234:237], v[16:19]
	v_mfma_f32_16x16x32_bf16 v[4:7], v[172:175], v[242:245], v[4:7]
	v_mfma_f32_16x16x32_bf16 v[0:3], v[180:183], v[242:245], v[0:3]
	s_barrier
	s_add_i32 s5, 0, 0x18000
	v_add_u32_e32 v112, s5, v154
	s_add_i32 s9, 0, 0x1c000
	ds_read_b128 v[148:151], v112
	ds_read_b128 v[156:159], v112 offset:1024
	ds_read_b128 v[160:163], v112 offset:2048
	ds_read_b128 v[164:167], v112 offset:3072
	v_add_u32_e32 v112, s9, v154
	ds_read_b128 v[168:171], v112
	ds_read_b128 v[172:175], v112 offset:1024
	ds_read_b128 v[176:179], v112 offset:2048
	ds_read_b128 v[180:183], v112 offset:3072
	s_add_u32 s6, s18, 0x80000
	s_addc_u32 s7, s19, 0
	s_mov_b32 m0, s61
	v_lshl_add_u64 v[118:119], s[6:7], 0, v[132:133]
	ds_read_b128 v[184:187], v155 offset:32768
	ds_read_b128 v[188:191], v155 offset:33792
	ds_read_b128 v[198:201], v155 offset:34816
	ds_read_b128 v[206:209], v155 offset:35840
	ds_read_b128 v[210:213], v155 offset:36864
	ds_read_b128 v[234:237], v155 offset:37888
	ds_read_b128 v[238:241], v155 offset:38912
	ds_read_b128 v[242:245], v155 offset:39936
	global_load_lds_dwordx4 v[118:119], off
	v_lshl_add_u64 v[118:119], s[6:7], 0, v[136:137]
	s_mov_b32 m0, s62
	s_nop 0
	global_load_lds_dwordx4 v[118:119], off
	s_waitcnt vmcnt(8)
	s_waitcnt lgkmcnt(0)
	s_barrier
	s_waitcnt lgkmcnt(0)
	v_mfma_f32_16x16x32_bf16 v[128:131], v[148:151], v[184:187], v[128:131]
	v_mfma_f32_16x16x32_bf16 v[124:127], v[160:163], v[184:187], v[124:127]
	v_mfma_f32_16x16x32_bf16 v[108:111], v[148:151], v[198:201], v[108:111]
	v_mfma_f32_16x16x32_bf16 v[104:107], v[160:163], v[198:201], v[104:107]
	v_mfma_f32_16x16x32_bf16 v[92:95], v[148:151], v[210:213], v[92:95]
	v_mfma_f32_16x16x32_bf16 v[88:91], v[160:163], v[210:213], v[88:91]
	v_mfma_f32_16x16x32_bf16 v[76:79], v[148:151], v[238:241], v[76:79]
	v_mfma_f32_16x16x32_bf16 v[72:75], v[160:163], v[238:241], v[72:75]
	v_mfma_f32_16x16x32_bf16 v[128:131], v[156:159], v[188:191], v[128:131]
	v_mfma_f32_16x16x32_bf16 v[124:127], v[164:167], v[188:191], v[124:127]
	v_mfma_f32_16x16x32_bf16 v[108:111], v[156:159], v[206:209], v[108:111]
	v_mfma_f32_16x16x32_bf16 v[104:107], v[164:167], v[206:209], v[104:107]
	v_mfma_f32_16x16x32_bf16 v[92:95], v[156:159], v[234:237], v[92:95]
	v_mfma_f32_16x16x32_bf16 v[88:91], v[164:167], v[234:237], v[88:91]
	v_mfma_f32_16x16x32_bf16 v[76:79], v[156:159], v[242:245], v[76:79]
	v_mfma_f32_16x16x32_bf16 v[72:75], v[164:167], v[242:245], v[72:75]
	v_mfma_f32_16x16x32_bf16 v[118:121], v[168:171], v[184:187], v[120:123]
	v_mfma_f32_16x16x32_bf16 v[114:117], v[176:179], v[184:187], v[114:117]
	v_mfma_f32_16x16x32_bf16 v[100:103], v[168:171], v[198:201], v[100:103]
	v_mfma_f32_16x16x32_bf16 v[96:99], v[176:179], v[198:201], v[96:99]
	v_mfma_f32_16x16x32_bf16 v[84:87], v[168:171], v[210:213], v[84:87]
	v_mfma_f32_16x16x32_bf16 v[80:83], v[176:179], v[210:213], v[80:83]
	v_mfma_f32_16x16x32_bf16 v[68:71], v[168:171], v[238:241], v[68:71]
	v_mfma_f32_16x16x32_bf16 v[64:67], v[176:179], v[238:241], v[64:67]
	v_mfma_f32_16x16x32_bf16 v[120:123], v[172:175], v[188:191], v[118:121]
	v_mfma_f32_16x16x32_bf16 v[116:119], v[180:183], v[188:191], v[114:117]
	v_mfma_f32_16x16x32_bf16 v[100:103], v[172:175], v[206:209], v[100:103]
	v_mfma_f32_16x16x32_bf16 v[96:99], v[180:183], v[206:209], v[96:99]
	v_mfma_f32_16x16x32_bf16 v[84:87], v[172:175], v[234:237], v[84:87]
	v_mfma_f32_16x16x32_bf16 v[80:83], v[180:183], v[234:237], v[80:83]
	v_mfma_f32_16x16x32_bf16 v[68:71], v[172:175], v[242:245], v[68:71]
	v_mfma_f32_16x16x32_bf16 v[64:67], v[180:183], v[242:245], v[64:67]
	s_barrier
	s_add_i32 s5, s5, s58
	v_lshl_add_u64 v[114:115], v[152:153], 0, s[48:49]
	s_mov_b32 m0, s5
	ds_read_b128 v[184:187], v155 offset:49152
	ds_read_b128 v[188:191], v155 offset:50176
	ds_read_b128 v[198:201], v155 offset:51200
	ds_read_b128 v[206:209], v155 offset:52224
	ds_read_b128 v[210:213], v155 offset:53248
	ds_read_b128 v[234:237], v155 offset:54272
	ds_read_b128 v[238:241], v155 offset:55296
	ds_read_b128 v[242:245], v155 offset:56320
	global_load_lds_dwordx4 v[114:115], off
	s_add_i32 m0, s5, 0x2000
	s_add_u32 s6, s16, 0x20080
	v_lshl_add_u64 v[114:115], v[192:193], 0, s[48:49]
	s_addc_u32 s7, s17, 0
	s_add_i32 s5, s9, s58
	global_load_lds_dwordx4 v[114:115], off
	v_lshl_add_u64 v[114:115], s[6:7], 0, v[134:135]
	s_mov_b32 m0, s5
	s_nop 0
	global_load_lds_dwordx4 v[114:115], off
	v_lshl_add_u64 v[114:115], s[6:7], 0, v[138:139]
	s_add_i32 m0, s5, 0x2000
	s_nop 0
	global_load_lds_dwordx4 v[114:115], off
	v_lshl_add_u64 v[114:115], v[246:247], 0, s[48:49]
	s_mov_b32 m0, s86
	s_nop 0
	global_load_lds_dwordx4 v[114:115], off
	v_lshl_add_u64 v[114:115], v[248:249], 0, s[48:49]
	s_mov_b32 m0, s87
	s_nop 0
	global_load_lds_dwordx4 v[114:115], off
	s_waitcnt vmcnt(8)
	s_waitcnt lgkmcnt(0)
	s_barrier
	s_waitcnt lgkmcnt(0)
	v_mfma_f32_16x16x32_bf16 v[60:63], v[148:151], v[184:187], v[60:63]
	v_mfma_f32_16x16x32_bf16 v[56:59], v[160:163], v[184:187], v[56:59]
	v_mfma_f32_16x16x32_bf16 v[44:47], v[148:151], v[198:201], v[44:47]
	v_mfma_f32_16x16x32_bf16 v[40:43], v[160:163], v[198:201], v[40:43]
	v_mfma_f32_16x16x32_bf16 v[28:31], v[148:151], v[210:213], v[28:31]
	v_mfma_f32_16x16x32_bf16 v[24:27], v[160:163], v[210:213], v[24:27]
	v_mfma_f32_16x16x32_bf16 v[12:15], v[148:151], v[238:241], v[12:15]
	v_mfma_f32_16x16x32_bf16 v[8:11], v[160:163], v[238:241], v[8:11]
	v_mfma_f32_16x16x32_bf16 v[60:63], v[156:159], v[188:191], v[60:63]
	v_mfma_f32_16x16x32_bf16 v[56:59], v[164:167], v[188:191], v[56:59]
	v_mfma_f32_16x16x32_bf16 v[44:47], v[156:159], v[206:209], v[44:47]
	v_mfma_f32_16x16x32_bf16 v[40:43], v[164:167], v[206:209], v[40:43]
	v_mfma_f32_16x16x32_bf16 v[28:31], v[156:159], v[234:237], v[28:31]
	v_mfma_f32_16x16x32_bf16 v[24:27], v[164:167], v[234:237], v[24:27]
	v_mfma_f32_16x16x32_bf16 v[12:15], v[156:159], v[242:245], v[12:15]
	v_mfma_f32_16x16x32_bf16 v[8:11], v[164:167], v[242:245], v[8:11]
	v_mfma_f32_16x16x32_bf16 v[52:55], v[168:171], v[184:187], v[52:55]
	v_mfma_f32_16x16x32_bf16 v[48:51], v[176:179], v[184:187], v[48:51]
	v_mfma_f32_16x16x32_bf16 v[36:39], v[168:171], v[198:201], v[36:39]
	v_mfma_f32_16x16x32_bf16 v[32:35], v[176:179], v[198:201], v[32:35]
	v_mfma_f32_16x16x32_bf16 v[20:23], v[168:171], v[210:213], v[20:23]
	v_mfma_f32_16x16x32_bf16 v[16:19], v[176:179], v[210:213], v[16:19]
	v_mfma_f32_16x16x32_bf16 v[4:7], v[168:171], v[238:241], v[4:7]
	v_mfma_f32_16x16x32_bf16 v[0:3], v[176:179], v[238:241], v[0:3]
	v_mfma_f32_16x16x32_bf16 v[52:55], v[172:175], v[188:191], v[52:55]
	v_mfma_f32_16x16x32_bf16 v[48:51], v[180:183], v[188:191], v[48:51]
	v_mfma_f32_16x16x32_bf16 v[36:39], v[172:175], v[206:209], v[36:39]
	v_mfma_f32_16x16x32_bf16 v[32:35], v[180:183], v[206:209], v[32:35]
	v_mfma_f32_16x16x32_bf16 v[20:23], v[172:175], v[234:237], v[20:23]
	v_mfma_f32_16x16x32_bf16 v[16:19], v[180:183], v[234:237], v[16:19]
	v_mfma_f32_16x16x32_bf16 v[4:7], v[172:175], v[242:245], v[4:7]
	v_mfma_f32_16x16x32_bf16 v[0:3], v[180:183], v[242:245], v[0:3]
	s_barrier
	s_cmp_lt_i32 s40, 14
	s_cbranch_scc1 .LBB1_623
	s_cmp_eq_u32 s40, 14
	s_cselect_b64 s[16:17], -1, 0
	s_cbranch_execz .LBB1_624
	s_branch .LBB1_625

.LBB1_651:
	v_readlane_b32 s1, v255, 43
	s_add_i32 s1, s1, 6
	s_cmp_lt_i32 s1, s77
	s_cselect_b64 s[16:17], -1, 0
	s_and_b64 s[2:3], s[42:43], s[16:17]
	s_andn2_b64 vcc, exec, s[2:3]
	s_cbranch_vccnz .LBB1_701
	s_setprio 0
	s_waitcnt vmcnt(0)
	s_waitcnt vmcnt(0)
	s_barrier
	s_mov_b64 s[2:3], exec
	v_readlane_b32 s6, v255, 20
	v_readlane_b32 s7, v255, 21
	s_and_b64 s[6:7], s[2:3], s[6:7]
	s_mov_b64 exec, s[6:7]
	s_cbranch_execz .LBB1_700
	v_readlane_b32 s5, v255, 18
	s_waitcnt vmcnt(0) expcnt(0) lgkmcnt(0)
	buffer_inv sc1
	s_nop 0
	v_mov_b32_e32 v0, s5
	ds_read_b32 v2, v0
	v_readlane_b32 s5, v255, 19
	s_waitcnt lgkmcnt(0)
	v_cmp_ne_u32_e32 vcc, 0, v2
	v_mov_b32_e32 v0, s5
	ds_read_b32 v0, v0
	s_cbranch_vccnz .LBB1_668
	v_readlane_b32 s10, v253, 8
	v_readlane_b32 s11, v253, 9
	s_load_dwordx2 s[6:7], s[10:11], 0x4
	s_waitcnt lgkmcnt(0)
	s_mul_i32 s5, s6, s33
	s_mul_i32 s5, s5, s7
	s_mov_b32 s6, 1
	s_branch .LBB1_656

.LBB1_711:
	s_and_b64 s[26:27], s[26:27], exec
	v_readlane_b32 s26, v255, 41
	v_readlane_b32 s80, v253, 10
	v_readlane_b32 s27, v255, 42
	s_mov_b32 s54, s26
	v_readlane_b32 s81, v253, 11
	v_readlane_b32 s84, v253, 14
	v_readlane_b32 s85, v253, 15
	s_mul_i32 s27, s54, 0x24000
	s_cselect_b32 s43, s81, 0
	s_cselect_b32 s42, s80, 0
	s_cselect_b32 s45, s85, 0
	s_cselect_b32 s44, s84, 0
	s_mul_hi_u32 s26, s26, 0x24000
	s_add_u32 s58, s37, s27
	v_readlane_b32 s27, v253, 52
	s_addc_u32 s59, s27, s26
	s_cmp_lg_u64 s[42:43], 0
	v_and_b32_e32 v15, 48, v8
	v_lshlrev_b32_e32 v16, 6, v8
	s_movk_i32 s27, 0x3c0
	v_lshlrev_b32_e32 v8, 2, v8
	s_cselect_b64 s[60:61], -1, 0
	s_and_b32 s37, s57, 3
	s_lshl_b32 s26, s36, 13
	v_and_or_b32 v15, v16, s27, v15
	v_and_b32_e32 v8, 32, v8
	s_add_i32 m0, s9, 0x18000
	v_lshl_add_u64 v[6:7], v[6:7], 0, s[48:49]
	s_lshl_b32 s54, s36, 6
	v_bitop3_b32 v16, v15, s26, v8 bitop3:0xde
	s_lshl_b32 s26, s37, 12
	s_waitcnt vmcnt(2)
	s_barrier
	global_load_lds_dwordx4 v[6:7], off
	v_lshl_add_u64 v[4:5], v[4:5], 0, s[48:49]
	s_add_i32 m0, s9, 0x1a000
	s_add_i32 s55, s9, 0x8000
	s_add_i32 s56, s9, 0xa000
	v_bitop3_b32 v170, v15, s26, v8 bitop3:0xde
	global_load_lds_dwordx4 v[4:5], off
	v_lshl_add_u64 v[0:1], v[0:1], 0, s[48:49]
	s_mov_b32 m0, s55
	s_add_u32 s26, s52, 0x20080
	global_load_lds_dwordx4 v[0:1], off
	v_lshl_add_u64 v[0:1], v[2:3], 0, s[48:49]
	s_mov_b32 m0, s56
	s_addc_u32 s27, s53, 0
	global_load_lds_dwordx4 v[0:1], off
	s_add_i32 m0, s9, 0x1c000
	v_lshl_add_u64 v[0:1], s[26:27], 0, v[148:149]
	global_load_lds_dwordx4 v[0:1], off
	v_lshl_add_u64 v[0:1], s[26:27], 0, v[152:153]
	s_add_i32 m0, s9, 0x1e000
	v_readlane_b32 s95, v253, 25
	global_load_lds_dwordx4 v[0:1], off
	v_lshlrev_b32_e32 v0, 15, v9
	v_and_b32_e32 v0, 0xffff0000, v0
	v_lshl_add_u32 v0, v10, 12, v0
	v_and_b32_e32 v1, 1, v9
	v_lshl_or_b32 v0, v1, 6, v0
	v_lshl_add_u32 v154, v11, 1, v0
	v_lshlrev_b32_e32 v0, 15, v12
	v_and_b32_e32 v0, 0xffff0000, v0
	s_waitcnt vmcnt(6)
	v_lshl_add_u32 v0, v13, 12, v0
	v_and_b32_e32 v1, 1, v12
	s_cmp_lt_u32 s57, 4
	s_cbranch_scc0 .Lgp_4
	s_setprio 1
.Lgp_4:
	v_lshl_or_b32 v0, v1, 6, v0
	v_readlane_b32 s64, v255, 27
	s_mov_b32 s25, 0
	s_cselect_b64 s[26:27], -1, 0
	s_lshl_b32 s57, s37, 6
	s_ashr_i32 s66, s1, 31
	v_mov_b32_e32 v155, v113
	v_lshl_add_u32 v156, v14, 1, v0
	v_mov_b32_e32 v157, v113
	v_add_u32_e32 v171, 0, v16
	v_readlane_b32 s65, v255, 28
	v_readlane_b32 s95, v255, 37
	v_readlane_b32 s82, v253, 12
	v_readlane_b32 s83, v253, 13
	v_readlane_b32 s86, v253, 16
	v_readlane_b32 s87, v253, 17
	v_readlane_b32 s88, v253, 18
	v_readlane_b32 s89, v253, 19
	v_readlane_b32 s90, v253, 20
	v_readlane_b32 s91, v253, 21
	v_readlane_b32 s92, v253, 22
	v_readlane_b32 s93, v253, 23
	v_readlane_b32 s94, v253, 24
	s_barrier
	s_branch .LBB1_714

.LBB1_721:
	s_add_u32 s82, s40, 0xfff80080
	s_addc_u32 s83, s41, -1
	s_add_i32 s92, 0, 0x10000
	s_cmp_eq_u32 s91, 28
	s_cselect_b32 s85, s39, s83
	s_cselect_b32 s84, s63, s82
	v_add_u32_e32 v112, s92, v170
	s_cselect_b32 s83, s72, s90
	s_cselect_b32 s82, s86, s87
	s_add_i32 s94, 0, 0x14000
	ds_read_b128 v[130:133], v112
	ds_read_b128 v[134:137], v112 offset:1024
	ds_read_b128 v[138:141], v112 offset:2048
	ds_read_b128 v[142:145], v112 offset:3072
	v_add_u32_e32 v112, s94, v170
	ds_read_b128 v[158:161], v112
	ds_read_b128 v[162:165], v112 offset:1024
	ds_read_b128 v[166:169], v112 offset:2048
	ds_read_b128 v[172:175], v112 offset:3072
	v_lshl_add_u64 v[192:193], s[40:41], 0, v[154:155]
	s_add_i32 m0, s9, 0xc000
	ds_read_b128 v[176:179], v171
	ds_read_b128 v[180:183], v171 offset:1024
	ds_read_b128 v[184:187], v171 offset:2048
	ds_read_b128 v[188:191], v171 offset:3072
	ds_read_b128 v[198:201], v171 offset:4096
	ds_read_b128 v[206:209], v171 offset:5120
	ds_read_b128 v[210:213], v171 offset:6144
	ds_read_b128 v[234:237], v171 offset:7168
	global_load_lds_dwordx4 v[192:193], off
	v_lshl_add_u64 v[192:193], s[40:41], 0, v[156:157]
	s_add_i32 m0, s9, 0xe000
	s_nop 0
	global_load_lds_dwordx4 v[192:193], off
	s_waitcnt vmcnt(8)
	s_waitcnt lgkmcnt(0)
	s_barrier
	s_waitcnt lgkmcnt(0)
	v_mfma_f32_16x16x32_bf16 v[126:129], v[130:133], v[176:179], v[126:129]
	v_mfma_f32_16x16x32_bf16 v[122:125], v[138:141], v[176:179], v[122:125]
	v_mfma_f32_16x16x32_bf16 v[108:111], v[130:133], v[184:187], v[108:111]
	v_mfma_f32_16x16x32_bf16 v[104:107], v[138:141], v[184:187], v[104:107]
	v_mfma_f32_16x16x32_bf16 v[92:95], v[130:133], v[198:201], v[92:95]
	v_mfma_f32_16x16x32_bf16 v[88:91], v[138:141], v[198:201], v[88:91]
	v_mfma_f32_16x16x32_bf16 v[76:79], v[130:133], v[210:213], v[76:79]
	v_mfma_f32_16x16x32_bf16 v[72:75], v[138:141], v[210:213], v[72:75]
	v_mfma_f32_16x16x32_bf16 v[126:129], v[134:137], v[180:183], v[126:129]
	v_mfma_f32_16x16x32_bf16 v[122:125], v[142:145], v[180:183], v[122:125]
	v_mfma_f32_16x16x32_bf16 v[108:111], v[134:137], v[188:191], v[108:111]
	v_mfma_f32_16x16x32_bf16 v[104:107], v[142:145], v[188:191], v[104:107]
	v_mfma_f32_16x16x32_bf16 v[92:95], v[134:137], v[206:209], v[92:95]
	v_mfma_f32_16x16x32_bf16 v[88:91], v[142:145], v[206:209], v[88:91]
	v_mfma_f32_16x16x32_bf16 v[76:79], v[134:137], v[234:237], v[76:79]
	v_mfma_f32_16x16x32_bf16 v[72:75], v[142:145], v[234:237], v[72:75]
	v_mfma_f32_16x16x32_bf16 v[118:121], v[158:161], v[176:179], v[118:121]
	v_mfma_f32_16x16x32_bf16 v[114:117], v[166:169], v[176:179], v[114:117]
	v_mfma_f32_16x16x32_bf16 v[100:103], v[158:161], v[184:187], v[100:103]
	v_mfma_f32_16x16x32_bf16 v[96:99], v[166:169], v[184:187], v[96:99]
	v_mfma_f32_16x16x32_bf16 v[84:87], v[158:161], v[198:201], v[84:87]
	v_mfma_f32_16x16x32_bf16 v[80:83], v[166:169], v[198:201], v[80:83]
	v_mfma_f32_16x16x32_bf16 v[68:71], v[158:161], v[210:213], v[68:71]
	v_mfma_f32_16x16x32_bf16 v[64:67], v[166:169], v[210:213], v[64:67]
	v_mfma_f32_16x16x32_bf16 v[118:121], v[162:165], v[180:183], v[118:121]
	v_mfma_f32_16x16x32_bf16 v[114:117], v[172:175], v[180:183], v[114:117]
	v_mfma_f32_16x16x32_bf16 v[100:103], v[162:165], v[188:191], v[100:103]
	v_mfma_f32_16x16x32_bf16 v[96:99], v[172:175], v[188:191], v[96:99]
	v_mfma_f32_16x16x32_bf16 v[84:87], v[162:165], v[206:209], v[84:87]
	v_mfma_f32_16x16x32_bf16 v[80:83], v[172:175], v[206:209], v[80:83]
	v_mfma_f32_16x16x32_bf16 v[68:71], v[162:165], v[234:237], v[68:71]
	v_mfma_f32_16x16x32_bf16 v[64:67], v[172:175], v[234:237], v[64:67]
	s_barrier
	s_add_i32 s92, s92, s7
	v_lshl_add_u64 v[192:193], s[82:83], 0, v[148:149]
	s_mov_b32 m0, s92
	ds_read_b128 v[176:179], v171 offset:16384
	ds_read_b128 v[180:183], v171 offset:17408
	ds_read_b128 v[184:187], v171 offset:18432
	ds_read_b128 v[188:191], v171 offset:19456
	ds_read_b128 v[198:201], v171 offset:20480
	ds_read_b128 v[206:209], v171 offset:21504
	ds_read_b128 v[210:213], v171 offset:22528
	ds_read_b128 v[234:237], v171 offset:23552
	global_load_lds_dwordx4 v[192:193], off
	s_add_i32 m0, s92, 0x2000
	s_add_u32 s92, s82, 0x20000
	v_lshl_add_u64 v[238:239], s[82:83], 0, v[152:153]
	s_addc_u32 s93, s83, 0
	s_add_i32 s94, s94, s7
	global_load_lds_dwordx4 v[238:239], off
	v_lshl_add_u64 v[240:241], s[92:93], 0, v[148:149]
	s_mov_b32 m0, s94
	v_lshl_add_u64 v[242:243], s[84:85], 0, v[150:151]
	global_load_lds_dwordx4 v[240:241], off
	v_lshl_add_u64 v[240:241], s[92:93], 0, v[152:153]
	s_add_i32 m0, s94, 0x2000
	s_nop 0
	global_load_lds_dwordx4 v[240:241], off
	v_lshl_add_u64 v[240:241], s[84:85], 0, v[146:147]
	s_mov_b32 m0, s9
	s_nop 0
	global_load_lds_dwordx4 v[240:241], off
	s_mov_b32 m0, s10
	s_nop 0
	global_load_lds_dwordx4 v[242:243], off
	s_waitcnt vmcnt(8)
	s_waitcnt lgkmcnt(0)
	s_barrier
	s_waitcnt lgkmcnt(0)
	v_mfma_f32_16x16x32_bf16 v[60:63], v[130:133], v[176:179], v[60:63]
	v_mfma_f32_16x16x32_bf16 v[56:59], v[138:141], v[176:179], v[56:59]
	v_mfma_f32_16x16x32_bf16 v[44:47], v[130:133], v[184:187], v[44:47]
	v_mfma_f32_16x16x32_bf16 v[40:43], v[138:141], v[184:187], v[40:43]
	v_mfma_f32_16x16x32_bf16 v[28:31], v[130:133], v[198:201], v[28:31]
	v_mfma_f32_16x16x32_bf16 v[24:27], v[138:141], v[198:201], v[24:27]
	v_mfma_f32_16x16x32_bf16 v[12:15], v[130:133], v[210:213], v[12:15]
	v_mfma_f32_16x16x32_bf16 v[8:11], v[138:141], v[210:213], v[8:11]
	v_mfma_f32_16x16x32_bf16 v[60:63], v[134:137], v[180:183], v[60:63]
	v_mfma_f32_16x16x32_bf16 v[56:59], v[142:145], v[180:183], v[56:59]
	v_mfma_f32_16x16x32_bf16 v[44:47], v[134:137], v[188:191], v[44:47]
	v_mfma_f32_16x16x32_bf16 v[40:43], v[142:145], v[188:191], v[40:43]
	v_mfma_f32_16x16x32_bf16 v[28:31], v[134:137], v[206:209], v[28:31]
	v_mfma_f32_16x16x32_bf16 v[24:27], v[142:145], v[206:209], v[24:27]
	v_mfma_f32_16x16x32_bf16 v[12:15], v[134:137], v[234:237], v[12:15]
	v_mfma_f32_16x16x32_bf16 v[8:11], v[142:145], v[234:237], v[8:11]
	v_mfma_f32_16x16x32_bf16 v[52:55], v[158:161], v[176:179], v[52:55]
	v_mfma_f32_16x16x32_bf16 v[48:51], v[166:169], v[176:179], v[48:51]
	v_mfma_f32_16x16x32_bf16 v[36:39], v[158:161], v[184:187], v[36:39]
	v_mfma_f32_16x16x32_bf16 v[32:35], v[166:169], v[184:187], v[32:35]
	v_mfma_f32_16x16x32_bf16 v[20:23], v[158:161], v[198:201], v[20:23]
	v_mfma_f32_16x16x32_bf16 v[16:19], v[166:169], v[198:201], v[16:19]
	v_mfma_f32_16x16x32_bf16 v[4:7], v[158:161], v[210:213], v[4:7]
	v_mfma_f32_16x16x32_bf16 v[0:3], v[166:169], v[210:213], v[0:3]
	v_mfma_f32_16x16x32_bf16 v[52:55], v[162:165], v[180:183], v[52:55]
	v_mfma_f32_16x16x32_bf16 v[48:51], v[172:175], v[180:183], v[48:51]
	v_mfma_f32_16x16x32_bf16 v[36:39], v[162:165], v[188:191], v[36:39]
	v_mfma_f32_16x16x32_bf16 v[32:35], v[172:175], v[188:191], v[32:35]
	v_mfma_f32_16x16x32_bf16 v[20:23], v[162:165], v[206:209], v[20:23]
	v_mfma_f32_16x16x32_bf16 v[16:19], v[172:175], v[206:209], v[16:19]
	v_mfma_f32_16x16x32_bf16 v[4:7], v[162:165], v[234:237], v[4:7]
	v_mfma_f32_16x16x32_bf16 v[0:3], v[172:175], v[234:237], v[0:3]
	s_barrier
	s_add_i32 s92, 0, 0x18000
	v_add_u32_e32 v112, s92, v170
	s_add_i32 s93, 0, 0x1c000
	ds_read_b128 v[130:133], v112
	ds_read_b128 v[134:137], v112 offset:1024
	ds_read_b128 v[138:141], v112 offset:2048
	ds_read_b128 v[142:145], v112 offset:3072
	v_add_u32_e32 v112, s93, v170
	ds_read_b128 v[158:161], v112
	ds_read_b128 v[162:165], v112 offset:1024
	ds_read_b128 v[166:169], v112 offset:2048
	ds_read_b128 v[172:175], v112 offset:3072
	s_add_u32 s84, s84, 0x80000
	s_addc_u32 s85, s85, 0
	s_mov_b32 m0, s11
	v_lshl_add_u64 v[244:245], s[84:85], 0, v[146:147]
	ds_read_b128 v[176:179], v171 offset:32768
	ds_read_b128 v[180:183], v171 offset:33792
	ds_read_b128 v[184:187], v171 offset:34816
	ds_read_b128 v[188:191], v171 offset:35840
	ds_read_b128 v[198:201], v171 offset:36864
	ds_read_b128 v[206:209], v171 offset:37888
	ds_read_b128 v[210:213], v171 offset:38912
	ds_read_b128 v[234:237], v171 offset:39936
	global_load_lds_dwordx4 v[244:245], off
	v_lshl_add_u64 v[244:245], s[84:85], 0, v[150:151]
	s_mov_b32 m0, s24
	s_nop 0
	global_load_lds_dwordx4 v[244:245], off
	s_waitcnt vmcnt(8)
	s_waitcnt lgkmcnt(0)
	s_barrier
	s_waitcnt lgkmcnt(0)
	v_mfma_f32_16x16x32_bf16 v[126:129], v[130:133], v[176:179], v[126:129]
	v_mfma_f32_16x16x32_bf16 v[122:125], v[138:141], v[176:179], v[122:125]
	v_mfma_f32_16x16x32_bf16 v[108:111], v[130:133], v[184:187], v[108:111]
	v_mfma_f32_16x16x32_bf16 v[104:107], v[138:141], v[184:187], v[104:107]
	v_mfma_f32_16x16x32_bf16 v[92:95], v[130:133], v[198:201], v[92:95]
	v_mfma_f32_16x16x32_bf16 v[88:91], v[138:141], v[198:201], v[88:91]
	v_mfma_f32_16x16x32_bf16 v[76:79], v[130:133], v[210:213], v[76:79]
	v_mfma_f32_16x16x32_bf16 v[72:75], v[138:141], v[210:213], v[72:75]
	v_mfma_f32_16x16x32_bf16 v[126:129], v[134:137], v[180:183], v[126:129]
	v_mfma_f32_16x16x32_bf16 v[122:125], v[142:145], v[180:183], v[122:125]
	v_mfma_f32_16x16x32_bf16 v[108:111], v[134:137], v[188:191], v[108:111]
	v_mfma_f32_16x16x32_bf16 v[104:107], v[142:145], v[188:191], v[104:107]
	v_mfma_f32_16x16x32_bf16 v[92:95], v[134:137], v[206:209], v[92:95]
	v_mfma_f32_16x16x32_bf16 v[88:91], v[142:145], v[206:209], v[88:91]
	v_mfma_f32_16x16x32_bf16 v[76:79], v[134:137], v[234:237], v[76:79]
	v_mfma_f32_16x16x32_bf16 v[72:75], v[142:145], v[234:237], v[72:75]
	v_mfma_f32_16x16x32_bf16 v[118:121], v[158:161], v[176:179], v[118:121]
	v_mfma_f32_16x16x32_bf16 v[114:117], v[166:169], v[176:179], v[114:117]
	v_mfma_f32_16x16x32_bf16 v[100:103], v[158:161], v[184:187], v[100:103]
	v_mfma_f32_16x16x32_bf16 v[96:99], v[166:169], v[184:187], v[96:99]
	v_mfma_f32_16x16x32_bf16 v[84:87], v[158:161], v[198:201], v[84:87]
	v_mfma_f32_16x16x32_bf16 v[80:83], v[166:169], v[198:201], v[80:83]
	v_mfma_f32_16x16x32_bf16 v[68:71], v[158:161], v[210:213], v[68:71]
	v_mfma_f32_16x16x32_bf16 v[64:67], v[166:169], v[210:213], v[64:67]
	v_mfma_f32_16x16x32_bf16 v[118:121], v[162:165], v[180:183], v[118:121]
	v_mfma_f32_16x16x32_bf16 v[114:117], v[172:175], v[180:183], v[114:117]
	v_mfma_f32_16x16x32_bf16 v[100:103], v[162:165], v[188:191], v[100:103]
	v_mfma_f32_16x16x32_bf16 v[96:99], v[172:175], v[188:191], v[96:99]
	v_mfma_f32_16x16x32_bf16 v[84:87], v[162:165], v[206:209], v[84:87]
	v_mfma_f32_16x16x32_bf16 v[80:83], v[172:175], v[206:209], v[80:83]
	v_mfma_f32_16x16x32_bf16 v[68:71], v[162:165], v[234:237], v[68:71]
	v_mfma_f32_16x16x32_bf16 v[64:67], v[172:175], v[234:237], v[64:67]
	s_barrier
	s_add_i32 s84, s92, s7
	v_lshl_add_u64 v[192:193], v[192:193], 0, s[48:49]
	s_mov_b32 m0, s84
	ds_read_b128 v[176:179], v171 offset:49152
	ds_read_b128 v[180:183], v171 offset:50176
	ds_read_b128 v[184:187], v171 offset:51200
	ds_read_b128 v[188:191], v171 offset:52224
	ds_read_b128 v[198:201], v171 offset:53248
	ds_read_b128 v[206:209], v171 offset:54272
	ds_read_b128 v[210:213], v171 offset:55296
	ds_read_b128 v[234:237], v171 offset:56320
	global_load_lds_dwordx4 v[192:193], off
	s_add_i32 m0, s84, 0x2000
	s_add_u32 s82, s82, 0x20080
	v_lshl_add_u64 v[192:193], v[238:239], 0, s[48:49]
	s_addc_u32 s83, s83, 0
	s_add_i32 s84, s93, s7
	global_load_lds_dwordx4 v[192:193], off
	v_lshl_add_u64 v[192:193], s[82:83], 0, v[148:149]
	s_mov_b32 m0, s84
	s_nop 0
	global_load_lds_dwordx4 v[192:193], off
	v_lshl_add_u64 v[192:193], s[82:83], 0, v[152:153]
	s_add_i32 m0, s84, 0x2000
	s_nop 0
	global_load_lds_dwordx4 v[192:193], off
	v_lshl_add_u64 v[192:193], v[240:241], 0, s[48:49]
	s_mov_b32 m0, s55
	s_nop 0
	global_load_lds_dwordx4 v[192:193], off
	v_lshl_add_u64 v[192:193], v[242:243], 0, s[48:49]
	s_mov_b32 m0, s56
	s_nop 0
	global_load_lds_dwordx4 v[192:193], off
	s_waitcnt vmcnt(8)
	s_waitcnt lgkmcnt(0)
	s_barrier
	s_waitcnt lgkmcnt(0)
	v_mfma_f32_16x16x32_bf16 v[60:63], v[130:133], v[176:179], v[60:63]
	v_mfma_f32_16x16x32_bf16 v[56:59], v[138:141], v[176:179], v[56:59]
	v_mfma_f32_16x16x32_bf16 v[44:47], v[130:133], v[184:187], v[44:47]
	v_mfma_f32_16x16x32_bf16 v[40:43], v[138:141], v[184:187], v[40:43]
	v_mfma_f32_16x16x32_bf16 v[28:31], v[130:133], v[198:201], v[28:31]
	v_mfma_f32_16x16x32_bf16 v[24:27], v[138:141], v[198:201], v[24:27]
	v_mfma_f32_16x16x32_bf16 v[12:15], v[130:133], v[210:213], v[12:15]
	v_mfma_f32_16x16x32_bf16 v[8:11], v[138:141], v[210:213], v[8:11]
	v_mfma_f32_16x16x32_bf16 v[60:63], v[134:137], v[180:183], v[60:63]
	v_mfma_f32_16x16x32_bf16 v[56:59], v[142:145], v[180:183], v[56:59]
	v_mfma_f32_16x16x32_bf16 v[44:47], v[134:137], v[188:191], v[44:47]
	v_mfma_f32_16x16x32_bf16 v[40:43], v[142:145], v[188:191], v[40:43]
	v_mfma_f32_16x16x32_bf16 v[28:31], v[134:137], v[206:209], v[28:31]
	v_mfma_f32_16x16x32_bf16 v[24:27], v[142:145], v[206:209], v[24:27]
	v_mfma_f32_16x16x32_bf16 v[12:15], v[134:137], v[234:237], v[12:15]
	v_mfma_f32_16x16x32_bf16 v[8:11], v[142:145], v[234:237], v[8:11]
	v_mfma_f32_16x16x32_bf16 v[52:55], v[158:161], v[176:179], v[52:55]
	v_mfma_f32_16x16x32_bf16 v[48:51], v[166:169], v[176:179], v[48:51]
	v_mfma_f32_16x16x32_bf16 v[36:39], v[158:161], v[184:187], v[36:39]
	v_mfma_f32_16x16x32_bf16 v[32:35], v[166:169], v[184:187], v[32:35]
	v_mfma_f32_16x16x32_bf16 v[20:23], v[158:161], v[198:201], v[20:23]
	v_mfma_f32_16x16x32_bf16 v[16:19], v[166:169], v[198:201], v[16:19]
	v_mfma_f32_16x16x32_bf16 v[4:7], v[158:161], v[210:213], v[4:7]
	v_mfma_f32_16x16x32_bf16 v[0:3], v[166:169], v[210:213], v[0:3]
	v_mfma_f32_16x16x32_bf16 v[52:55], v[162:165], v[180:183], v[52:55]
	v_mfma_f32_16x16x32_bf16 v[48:51], v[172:175], v[180:183], v[48:51]
	v_mfma_f32_16x16x32_bf16 v[36:39], v[162:165], v[188:191], v[36:39]
	v_mfma_f32_16x16x32_bf16 v[32:35], v[172:175], v[188:191], v[32:35]
	v_mfma_f32_16x16x32_bf16 v[20:23], v[162:165], v[206:209], v[20:23]
	v_mfma_f32_16x16x32_bf16 v[16:19], v[172:175], v[206:209], v[16:19]
	v_mfma_f32_16x16x32_bf16 v[4:7], v[162:165], v[234:237], v[4:7]
	v_mfma_f32_16x16x32_bf16 v[0:3], v[172:175], v[234:237], v[0:3]
	s_barrier
	s_add_i32 s91, s91, 2
	s_add_u32 s40, s40, 0x100
	s_addc_u32 s41, s41, 0
	s_add_u32 s87, s87, 0x100
	s_addc_u32 s90, s90, 0
	s_cmp_gt_u32 s91, 29
	s_cbranch_scc0 .LBB1_721
	s_and_b64 vcc, exec, s[26:27]
	s_cbranch_vccz .LBB1_724
	s_barrier

.LBB1_815:
	v_readlane_b32 s1, v255, 43
	s_add_i32 s1, s1, 7
	s_cmp_lt_i32 s1, s77
	s_cselect_b64 s[16:17], -1, 0
	s_and_b64 s[2:3], s[2:3], s[16:17]
	s_andn2_b64 vcc, exec, s[2:3]
	s_cbranch_vccnz .LBB1_865
	s_setprio 0
	s_waitcnt vmcnt(0)
	s_waitcnt vmcnt(0)
	s_barrier
	s_mov_b64 s[2:3], exec
	v_readlane_b32 s6, v255, 20
	v_readlane_b32 s7, v255, 21
	s_and_b64 s[6:7], s[2:3], s[6:7]
	s_mov_b64 exec, s[6:7]
	s_cbranch_execz .LBB1_864
	v_readlane_b32 s5, v255, 18
	s_waitcnt vmcnt(0) expcnt(0) lgkmcnt(0)
	buffer_inv sc1
	s_nop 0
	v_mov_b32_e32 v0, s5
	ds_read_b32 v2, v0
	v_readlane_b32 s5, v255, 19
	s_waitcnt lgkmcnt(0)
	v_cmp_ne_u32_e32 vcc, 0, v2
	v_mov_b32_e32 v0, s5
	ds_read_b32 v0, v0
	s_cbranch_vccnz .LBB1_832
	v_readlane_b32 s10, v253, 8
	v_readlane_b32 s11, v253, 9
	s_load_dwordx2 s[6:7], s[10:11], 0x4
	s_waitcnt lgkmcnt(0)
	s_mul_i32 s5, s6, s33
	s_mul_i32 s5, s5, s7
	s_mov_b32 s6, 1
	s_branch .LBB1_820

.LBB1_873:
	v_readlane_b32 s1, v255, 43
	s_add_i32 s1, s1, 8
	s_cmp_ge_i32 s1, s77
	s_cbranch_scc1 .LBB1_885
	s_setprio 0
	s_waitcnt vmcnt(0)
	s_waitcnt vmcnt(0)
	s_barrier
	s_mov_b64 s[2:3], exec
	v_readlane_b32 s6, v255, 20
	v_readlane_b32 s7, v255, 21
	s_and_b64 s[6:7], s[2:3], s[6:7]
	s_movk_i32 s25, 0x120
	s_mov_b64 exec, s[6:7]
	s_cbranch_execz .LBB1_923
	v_readlane_b32 s5, v255, 18
	s_waitcnt vmcnt(0) expcnt(0) lgkmcnt(0)
	buffer_inv sc1
	s_nop 0
	v_mov_b32_e32 v0, s5
	ds_read_b32 v2, v0
	v_readlane_b32 s5, v255, 19
	s_waitcnt lgkmcnt(0)
	v_cmp_ne_u32_e32 vcc, 0, v2
	v_mov_b32_e32 v0, s5
	ds_read_b32 v0, v0
	s_cbranch_vccnz .LBB1_891
	v_readlane_b32 s10, v253, 8
	v_readlane_b32 s11, v253, 9
	s_load_dwordx2 s[6:7], s[10:11], 0x4
	s_waitcnt lgkmcnt(0)
	s_mul_i32 s5, s6, s33
	s_mul_i32 s5, s5, s7
	s_mov_b32 s6, 1
	s_branch .LBB1_878

.LBB1_930:
	v_readlane_b32 s16, v255, 41
	v_readlane_b32 s17, v255, 42
	v_readlane_b32 s80, v253, 0
	s_mul_i32 s16, s16, 0x8400
	s_mov_b32 s17, s73
	v_readlane_b32 s82, v253, 2
	v_readlane_b32 s83, v253, 3
	s_lshl_b64 s[16:17], s[16:17], 2
	s_mov_b64 s[54:55], s[82:83]
	s_add_u32 s78, s54, s16
	v_and_b32_e32 v15, 48, v8
	v_lshlrev_b32_e32 v16, 6, v8
	s_movk_i32 s16, 0x3c0
	v_lshlrev_b32_e32 v8, 2, v8
	s_addc_u32 s79, s55, s17
	s_and_b32 s18, s10, 3
	s_lshl_b32 s9, s1, 13
	v_and_or_b32 v15, v16, s16, v15
	v_and_b32_e32 v8, 32, v8
	v_bitop3_b32 v16, v15, s9, v8 bitop3:0xde
	s_lshl_b32 s9, s18, 12
	s_add_i32 m0, s7, 0x18000
	v_lshl_add_u64 v[6:7], v[6:7], 0, s[48:49]
	s_lshr_b32 s89, s72, 3
	s_lshl_b32 s91, s1, 6
	s_lshl_b32 s66, s18, 5
	v_bitop3_b32 v166, v15, s9, v8 bitop3:0xde
	s_waitcnt vmcnt(2)
	s_barrier
	global_load_lds_dwordx4 v[6:7], off
	v_lshl_add_u64 v[4:5], v[4:5], 0, s[48:49]
	s_add_i32 m0, s7, 0x1a000
	s_add_i32 s67, s7, 0x8000
	s_add_i32 s9, s7, 0xa000
	global_load_lds_dwordx4 v[4:5], off
	v_lshl_add_u64 v[0:1], v[0:1], 0, s[48:49]
	s_mov_b32 m0, s67
	s_add_u32 s16, s38, 0x20080
	global_load_lds_dwordx4 v[0:1], off
	v_lshl_add_u64 v[0:1], v[2:3], 0, s[48:49]
	s_mov_b32 m0, s9
	s_addc_u32 s17, s39, 0
	global_load_lds_dwordx4 v[0:1], off
	s_add_i32 m0, s7, 0x1c000
	v_lshl_add_u64 v[0:1], s[16:17], 0, v[156:157]
	global_load_lds_dwordx4 v[0:1], off
	v_lshl_add_u64 v[0:1], s[16:17], 0, v[160:161]
	s_add_i32 m0, s7, 0x1e000
	v_readlane_b32 s81, v253, 1
	global_load_lds_dwordx4 v[0:1], off
	s_cmp_lt_u32 s10, 4
	s_cbranch_scc0 .Lgp_5
	s_setprio 1
.Lgp_5:
	v_lshlrev_b32_e32 v0, 15, v9
	s_cselect_b64 s[80:81], -1, 0
	s_lshl_b32 s16, s1, 8
	s_lshl_b32 s17, s18, 6
	v_and_b32_e32 v0, 0xffff0000, v0
	s_lshl_b32 s10, s1, 11
	s_or_b32 s54, s17, s16
	v_lshl_add_u32 v0, v10, 12, v0
	v_and_b32_e32 v1, 1, v9
	s_cmp_gt_i32 s1, 0
	v_lshl_or_b32 v0, v1, 6, v0
	v_readlane_b32 s84, v253, 4
	v_readlane_b32 s85, v253, 5
	s_cselect_b64 s[82:83], -1, 0
	s_cmp_lt_i32 s1, 3
	v_lshl_add_u32 v162, v11, 1, v0
	v_lshlrev_b32_e32 v0, 15, v12
	v_readlane_b32 s86, v253, 6
	v_readlane_b32 s87, v253, 7
	s_cselect_b64 s[84:85], -1, 0
	s_cmp_gt_i32 s1, -2
	v_and_b32_e32 v0, 0xffff0000, v0
	s_waitcnt vmcnt(6)
	s_cselect_b64 s[86:87], -1, 0
	s_cmp_lt_i32 s1, 1
	v_lshl_add_u32 v0, v13, 12, v0
	v_and_b32_e32 v1, 1, v12
	s_cselect_b64 s[58:59], -1, 0
	s_add_i32 s10, s10, 0
	v_lshl_or_b32 v0, v1, 6, v0
	s_mov_b32 s55, 0
	s_ashr_i32 s25, s57, 31
	s_add_i32 s90, s10, 0x20400
	s_add_i32 s68, s10, 0x20800
	s_add_i32 s56, s10, 0x20000
	s_add_i32 s10, s10, 0x20200
	v_mov_b32_e32 v163, v113
	v_lshl_add_u32 v164, v14, 1, v0
	v_mov_b32_e32 v165, v113
	v_add_u32_e32 v167, 0, v16
	s_barrier
	s_branch .LBB1_933

.LBB1_939:
	s_add_u32 s38, s26, 0xfff80080
	s_addc_u32 s39, s27, -1
	s_add_i32 s94, 0, 0x10000
	s_cmp_eq_u32 vcc_lo, 28
	s_cselect_b32 s41, s19, s39
	s_cselect_b32 s40, s31, s38
	v_add_u32_e32 v112, s94, v166
	s_cselect_b32 s39, s42, s45
	s_cselect_b32 s38, s43, s44
	s_add_i32 vcc_hi, 0, 0x14000
	ds_read_b128 v[130:133], v112
	ds_read_b128 v[134:137], v112 offset:1024
	ds_read_b128 v[138:141], v112 offset:2048
	ds_read_b128 v[142:145], v112 offset:3072
	v_add_u32_e32 v112, vcc_hi, v166
	ds_read_b128 v[146:149], v112
	ds_read_b128 v[150:153], v112 offset:1024
	ds_read_b128 v[168:171], v112 offset:2048
	ds_read_b128 v[172:175], v112 offset:3072
	v_lshl_add_u64 v[192:193], s[26:27], 0, v[162:163]
	s_add_i32 m0, s7, 0xc000
	ds_read_b128 v[176:179], v167
	ds_read_b128 v[180:183], v167 offset:1024
	ds_read_b128 v[184:187], v167 offset:2048
	ds_read_b128 v[188:191], v167 offset:3072
	ds_read_b128 v[198:201], v167 offset:4096
	ds_read_b128 v[206:209], v167 offset:5120
	ds_read_b128 v[210:213], v167 offset:6144
	ds_read_b128 v[234:237], v167 offset:7168
	global_load_lds_dwordx4 v[192:193], off
	v_lshl_add_u64 v[192:193], s[26:27], 0, v[164:165]
	s_add_i32 m0, s7, 0xe000
	s_nop 0
	global_load_lds_dwordx4 v[192:193], off
	s_waitcnt vmcnt(8)
	s_waitcnt lgkmcnt(0)
	s_barrier
	s_waitcnt lgkmcnt(0)
	v_mfma_f32_16x16x32_bf16 v[108:111], v[130:133], v[176:179], v[108:111]
	v_mfma_f32_16x16x32_bf16 v[84:87], v[138:141], v[176:179], v[84:87]
	v_mfma_f32_16x16x32_bf16 v[126:129], v[130:133], v[184:187], v[126:129]
	v_mfma_f32_16x16x32_bf16 v[92:95], v[138:141], v[184:187], v[92:95]
	v_mfma_f32_16x16x32_bf16 v[122:125], v[130:133], v[198:201], v[122:125]
	v_mfma_f32_16x16x32_bf16 v[88:91], v[138:141], v[198:201], v[88:91]
	v_mfma_f32_16x16x32_bf16 v[104:107], v[130:133], v[210:213], v[104:107]
	v_mfma_f32_16x16x32_bf16 v[76:79], v[138:141], v[210:213], v[76:79]
	v_mfma_f32_16x16x32_bf16 v[108:111], v[134:137], v[180:183], v[108:111]
	v_mfma_f32_16x16x32_bf16 v[84:87], v[142:145], v[180:183], v[84:87]
	v_mfma_f32_16x16x32_bf16 v[126:129], v[134:137], v[188:191], v[126:129]
	v_mfma_f32_16x16x32_bf16 v[92:95], v[142:145], v[188:191], v[92:95]
	v_mfma_f32_16x16x32_bf16 v[122:125], v[134:137], v[206:209], v[122:125]
	v_mfma_f32_16x16x32_bf16 v[88:91], v[142:145], v[206:209], v[88:91]
	v_mfma_f32_16x16x32_bf16 v[104:107], v[134:137], v[234:237], v[104:107]
	v_mfma_f32_16x16x32_bf16 v[76:79], v[142:145], v[234:237], v[76:79]
	v_mfma_f32_16x16x32_bf16 v[100:103], v[146:149], v[176:179], v[100:103]
	v_mfma_f32_16x16x32_bf16 v[68:71], v[168:171], v[176:179], v[68:71]
	v_mfma_f32_16x16x32_bf16 v[118:121], v[146:149], v[184:187], v[118:121]
	v_mfma_f32_16x16x32_bf16 v[80:83], v[168:171], v[184:187], v[80:83]
	v_mfma_f32_16x16x32_bf16 v[114:117], v[146:149], v[198:201], v[114:117]
	v_mfma_f32_16x16x32_bf16 v[72:75], v[168:171], v[198:201], v[72:75]
	v_mfma_f32_16x16x32_bf16 v[96:99], v[146:149], v[210:213], v[96:99]
	v_mfma_f32_16x16x32_bf16 v[64:67], v[168:171], v[210:213], v[64:67]
	v_mfma_f32_16x16x32_bf16 v[100:103], v[150:153], v[180:183], v[100:103]
	v_mfma_f32_16x16x32_bf16 v[68:71], v[172:175], v[180:183], v[68:71]
	v_mfma_f32_16x16x32_bf16 v[118:121], v[150:153], v[188:191], v[118:121]
	v_mfma_f32_16x16x32_bf16 v[80:83], v[172:175], v[188:191], v[80:83]
	v_mfma_f32_16x16x32_bf16 v[114:117], v[150:153], v[206:209], v[114:117]
	v_mfma_f32_16x16x32_bf16 v[72:75], v[172:175], v[206:209], v[72:75]
	v_mfma_f32_16x16x32_bf16 v[96:99], v[150:153], v[234:237], v[96:99]
	v_mfma_f32_16x16x32_bf16 v[64:67], v[172:175], v[234:237], v[64:67]
	s_barrier
	s_add_i32 s94, s94, s6
	v_lshl_add_u64 v[192:193], s[38:39], 0, v[156:157]
	s_mov_b32 m0, s94
	ds_read_b128 v[176:179], v167 offset:16384
	ds_read_b128 v[180:183], v167 offset:17408
	ds_read_b128 v[184:187], v167 offset:18432
	ds_read_b128 v[188:191], v167 offset:19456
	ds_read_b128 v[198:201], v167 offset:20480
	ds_read_b128 v[206:209], v167 offset:21504
	ds_read_b128 v[210:213], v167 offset:22528
	ds_read_b128 v[234:237], v167 offset:23552
	global_load_lds_dwordx4 v[192:193], off
	s_add_i32 m0, s94, 0x2000
	s_add_u32 s94, s38, 0x20000
	v_lshl_add_u64 v[238:239], s[38:39], 0, v[160:161]
	s_addc_u32 s95, s39, 0
	s_add_i32 vcc_hi, vcc_hi, s6
	global_load_lds_dwordx4 v[238:239], off
	v_lshl_add_u64 v[240:241], s[94:95], 0, v[156:157]
	s_mov_b32 m0, vcc_hi
	v_lshl_add_u64 v[242:243], s[40:41], 0, v[158:159]
	global_load_lds_dwordx4 v[240:241], off
	v_lshl_add_u64 v[240:241], s[94:95], 0, v[160:161]
	s_add_i32 m0, vcc_hi, 0x2000
	s_nop 0
	global_load_lds_dwordx4 v[240:241], off
	v_lshl_add_u64 v[240:241], s[40:41], 0, v[154:155]
	s_mov_b32 m0, s7
	s_nop 0
	global_load_lds_dwordx4 v[240:241], off
	s_mov_b32 m0, s2
	s_nop 0
	global_load_lds_dwordx4 v[242:243], off
	s_waitcnt vmcnt(8)
	s_waitcnt lgkmcnt(0)
	s_barrier
	s_waitcnt lgkmcnt(0)
	v_mfma_f32_16x16x32_bf16 v[52:55], v[130:133], v[176:179], v[52:55]
	v_mfma_f32_16x16x32_bf16 v[20:23], v[138:141], v[176:179], v[20:23]
	v_mfma_f32_16x16x32_bf16 v[60:63], v[130:133], v[184:187], v[60:63]
	v_mfma_f32_16x16x32_bf16 v[28:31], v[138:141], v[184:187], v[28:31]
	v_mfma_f32_16x16x32_bf16 v[56:59], v[130:133], v[198:201], v[56:59]
	v_mfma_f32_16x16x32_bf16 v[24:27], v[138:141], v[198:201], v[24:27]
	v_mfma_f32_16x16x32_bf16 v[48:51], v[130:133], v[210:213], v[48:51]
	v_mfma_f32_16x16x32_bf16 v[16:19], v[138:141], v[210:213], v[16:19]
	v_mfma_f32_16x16x32_bf16 v[52:55], v[134:137], v[180:183], v[52:55]
	v_mfma_f32_16x16x32_bf16 v[20:23], v[142:145], v[180:183], v[20:23]
	v_mfma_f32_16x16x32_bf16 v[60:63], v[134:137], v[188:191], v[60:63]
	v_mfma_f32_16x16x32_bf16 v[28:31], v[142:145], v[188:191], v[28:31]
	v_mfma_f32_16x16x32_bf16 v[56:59], v[134:137], v[206:209], v[56:59]
	v_mfma_f32_16x16x32_bf16 v[24:27], v[142:145], v[206:209], v[24:27]
	v_mfma_f32_16x16x32_bf16 v[48:51], v[134:137], v[234:237], v[48:51]
	v_mfma_f32_16x16x32_bf16 v[16:19], v[142:145], v[234:237], v[16:19]
	v_mfma_f32_16x16x32_bf16 v[36:39], v[146:149], v[176:179], v[36:39]
	v_mfma_f32_16x16x32_bf16 v[4:7], v[168:171], v[176:179], v[4:7]
	v_mfma_f32_16x16x32_bf16 v[44:47], v[146:149], v[184:187], v[44:47]
	v_mfma_f32_16x16x32_bf16 v[12:15], v[168:171], v[184:187], v[12:15]
	v_mfma_f32_16x16x32_bf16 v[40:43], v[146:149], v[198:201], v[40:43]
	v_mfma_f32_16x16x32_bf16 v[8:11], v[168:171], v[198:201], v[8:11]
	v_mfma_f32_16x16x32_bf16 v[32:35], v[146:149], v[210:213], v[32:35]
	v_mfma_f32_16x16x32_bf16 v[0:3], v[168:171], v[210:213], v[0:3]
	v_mfma_f32_16x16x32_bf16 v[36:39], v[150:153], v[180:183], v[36:39]
	v_mfma_f32_16x16x32_bf16 v[4:7], v[172:175], v[180:183], v[4:7]
	v_mfma_f32_16x16x32_bf16 v[44:47], v[150:153], v[188:191], v[44:47]
	v_mfma_f32_16x16x32_bf16 v[12:15], v[172:175], v[188:191], v[12:15]
	v_mfma_f32_16x16x32_bf16 v[40:43], v[150:153], v[206:209], v[40:43]
	v_mfma_f32_16x16x32_bf16 v[8:11], v[172:175], v[206:209], v[8:11]
	v_mfma_f32_16x16x32_bf16 v[32:35], v[150:153], v[234:237], v[32:35]
	v_mfma_f32_16x16x32_bf16 v[0:3], v[172:175], v[234:237], v[0:3]
	s_barrier
	s_add_i32 s94, 0, 0x18000
	v_add_u32_e32 v112, s94, v166
	s_add_i32 s95, 0, 0x1c000
	ds_read_b128 v[130:133], v112
	ds_read_b128 v[134:137], v112 offset:1024
	ds_read_b128 v[138:141], v112 offset:2048
	ds_read_b128 v[142:145], v112 offset:3072
	v_add_u32_e32 v112, s95, v166
	ds_read_b128 v[146:149], v112
	ds_read_b128 v[150:153], v112 offset:1024
	ds_read_b128 v[168:171], v112 offset:2048
	ds_read_b128 v[172:175], v112 offset:3072
	s_add_u32 s40, s40, 0x80000
	s_addc_u32 s41, s41, 0
	s_mov_b32 m0, s3
	v_lshl_add_u64 v[244:245], s[40:41], 0, v[154:155]
	ds_read_b128 v[176:179], v167 offset:32768
	ds_read_b128 v[180:183], v167 offset:33792
	ds_read_b128 v[184:187], v167 offset:34816
	ds_read_b128 v[188:191], v167 offset:35840
	ds_read_b128 v[198:201], v167 offset:36864
	ds_read_b128 v[206:209], v167 offset:37888
	ds_read_b128 v[210:213], v167 offset:38912
	ds_read_b128 v[234:237], v167 offset:39936
	global_load_lds_dwordx4 v[244:245], off
	v_lshl_add_u64 v[244:245], s[40:41], 0, v[158:159]
	s_mov_b32 m0, s5
	s_nop 0
	global_load_lds_dwordx4 v[244:245], off
	s_waitcnt vmcnt(8)
	s_waitcnt lgkmcnt(0)
	s_barrier
	s_waitcnt lgkmcnt(0)
	v_mfma_f32_16x16x32_bf16 v[108:111], v[130:133], v[176:179], v[108:111]
	v_mfma_f32_16x16x32_bf16 v[84:87], v[138:141], v[176:179], v[84:87]
	v_mfma_f32_16x16x32_bf16 v[126:129], v[130:133], v[184:187], v[126:129]
	v_mfma_f32_16x16x32_bf16 v[92:95], v[138:141], v[184:187], v[92:95]
	v_mfma_f32_16x16x32_bf16 v[122:125], v[130:133], v[198:201], v[122:125]
	v_mfma_f32_16x16x32_bf16 v[88:91], v[138:141], v[198:201], v[88:91]
	v_mfma_f32_16x16x32_bf16 v[104:107], v[130:133], v[210:213], v[104:107]
	v_mfma_f32_16x16x32_bf16 v[76:79], v[138:141], v[210:213], v[76:79]
	v_mfma_f32_16x16x32_bf16 v[108:111], v[134:137], v[180:183], v[108:111]
	v_mfma_f32_16x16x32_bf16 v[84:87], v[142:145], v[180:183], v[84:87]
	v_mfma_f32_16x16x32_bf16 v[126:129], v[134:137], v[188:191], v[126:129]
	v_mfma_f32_16x16x32_bf16 v[92:95], v[142:145], v[188:191], v[92:95]
	v_mfma_f32_16x16x32_bf16 v[122:125], v[134:137], v[206:209], v[122:125]
	v_mfma_f32_16x16x32_bf16 v[88:91], v[142:145], v[206:209], v[88:91]
	v_mfma_f32_16x16x32_bf16 v[104:107], v[134:137], v[234:237], v[104:107]
	v_mfma_f32_16x16x32_bf16 v[76:79], v[142:145], v[234:237], v[76:79]
	v_mfma_f32_16x16x32_bf16 v[100:103], v[146:149], v[176:179], v[100:103]
	v_mfma_f32_16x16x32_bf16 v[68:71], v[168:171], v[176:179], v[68:71]
	v_mfma_f32_16x16x32_bf16 v[118:121], v[146:149], v[184:187], v[118:121]
	v_mfma_f32_16x16x32_bf16 v[80:83], v[168:171], v[184:187], v[80:83]
	v_mfma_f32_16x16x32_bf16 v[114:117], v[146:149], v[198:201], v[114:117]
	v_mfma_f32_16x16x32_bf16 v[72:75], v[168:171], v[198:201], v[72:75]
	v_mfma_f32_16x16x32_bf16 v[96:99], v[146:149], v[210:213], v[96:99]
	v_mfma_f32_16x16x32_bf16 v[64:67], v[168:171], v[210:213], v[64:67]
	v_mfma_f32_16x16x32_bf16 v[100:103], v[150:153], v[180:183], v[100:103]
	v_mfma_f32_16x16x32_bf16 v[68:71], v[172:175], v[180:183], v[68:71]
	v_mfma_f32_16x16x32_bf16 v[118:121], v[150:153], v[188:191], v[118:121]
	v_mfma_f32_16x16x32_bf16 v[80:83], v[172:175], v[188:191], v[80:83]
	v_mfma_f32_16x16x32_bf16 v[114:117], v[150:153], v[206:209], v[114:117]
	v_mfma_f32_16x16x32_bf16 v[72:75], v[172:175], v[206:209], v[72:75]
	v_mfma_f32_16x16x32_bf16 v[96:99], v[150:153], v[234:237], v[96:99]
	v_mfma_f32_16x16x32_bf16 v[64:67], v[172:175], v[234:237], v[64:67]
	s_barrier
	s_add_i32 s40, s94, s6
	v_lshl_add_u64 v[192:193], v[192:193], 0, s[48:49]
	s_mov_b32 m0, s40
	ds_read_b128 v[176:179], v167 offset:49152
	ds_read_b128 v[180:183], v167 offset:50176
	ds_read_b128 v[184:187], v167 offset:51200
	ds_read_b128 v[188:191], v167 offset:52224
	ds_read_b128 v[198:201], v167 offset:53248
	ds_read_b128 v[206:209], v167 offset:54272
	ds_read_b128 v[210:213], v167 offset:55296
	ds_read_b128 v[234:237], v167 offset:56320
	global_load_lds_dwordx4 v[192:193], off
	s_add_i32 m0, s40, 0x2000
	s_add_u32 s38, s38, 0x20080
	v_lshl_add_u64 v[192:193], v[238:239], 0, s[48:49]
	s_addc_u32 s39, s39, 0
	s_add_i32 s40, s95, s6
	global_load_lds_dwordx4 v[192:193], off
	v_lshl_add_u64 v[192:193], s[38:39], 0, v[156:157]
	s_mov_b32 m0, s40
	s_nop 0
	global_load_lds_dwordx4 v[192:193], off
	v_lshl_add_u64 v[192:193], s[38:39], 0, v[160:161]
	s_add_i32 m0, s40, 0x2000
	s_nop 0
	global_load_lds_dwordx4 v[192:193], off
	v_lshl_add_u64 v[192:193], v[240:241], 0, s[48:49]
	s_mov_b32 m0, s67
	s_nop 0
	global_load_lds_dwordx4 v[192:193], off
	v_lshl_add_u64 v[192:193], v[242:243], 0, s[48:49]
	s_mov_b32 m0, s9
	s_nop 0
	global_load_lds_dwordx4 v[192:193], off
	s_waitcnt vmcnt(8)
	s_waitcnt lgkmcnt(0)
	s_barrier
	s_waitcnt lgkmcnt(0)
	v_mfma_f32_16x16x32_bf16 v[52:55], v[130:133], v[176:179], v[52:55]
	v_mfma_f32_16x16x32_bf16 v[20:23], v[138:141], v[176:179], v[20:23]
	v_mfma_f32_16x16x32_bf16 v[60:63], v[130:133], v[184:187], v[60:63]
	v_mfma_f32_16x16x32_bf16 v[28:31], v[138:141], v[184:187], v[28:31]
	v_mfma_f32_16x16x32_bf16 v[56:59], v[130:133], v[198:201], v[56:59]
	v_mfma_f32_16x16x32_bf16 v[24:27], v[138:141], v[198:201], v[24:27]
	v_mfma_f32_16x16x32_bf16 v[48:51], v[130:133], v[210:213], v[48:51]
	v_mfma_f32_16x16x32_bf16 v[16:19], v[138:141], v[210:213], v[16:19]
	v_mfma_f32_16x16x32_bf16 v[52:55], v[134:137], v[180:183], v[52:55]
	v_mfma_f32_16x16x32_bf16 v[20:23], v[142:145], v[180:183], v[20:23]
	v_mfma_f32_16x16x32_bf16 v[60:63], v[134:137], v[188:191], v[60:63]
	v_mfma_f32_16x16x32_bf16 v[28:31], v[142:145], v[188:191], v[28:31]
	v_mfma_f32_16x16x32_bf16 v[56:59], v[134:137], v[206:209], v[56:59]
	v_mfma_f32_16x16x32_bf16 v[24:27], v[142:145], v[206:209], v[24:27]
	v_mfma_f32_16x16x32_bf16 v[48:51], v[134:137], v[234:237], v[48:51]
	v_mfma_f32_16x16x32_bf16 v[16:19], v[142:145], v[234:237], v[16:19]
	v_mfma_f32_16x16x32_bf16 v[36:39], v[146:149], v[176:179], v[36:39]
	v_mfma_f32_16x16x32_bf16 v[4:7], v[168:171], v[176:179], v[4:7]
	v_mfma_f32_16x16x32_bf16 v[44:47], v[146:149], v[184:187], v[44:47]
	v_mfma_f32_16x16x32_bf16 v[12:15], v[168:171], v[184:187], v[12:15]
	v_mfma_f32_16x16x32_bf16 v[40:43], v[146:149], v[198:201], v[40:43]
	v_mfma_f32_16x16x32_bf16 v[8:11], v[168:171], v[198:201], v[8:11]
	v_mfma_f32_16x16x32_bf16 v[32:35], v[146:149], v[210:213], v[32:35]
	v_mfma_f32_16x16x32_bf16 v[0:3], v[168:171], v[210:213], v[0:3]
	v_mfma_f32_16x16x32_bf16 v[36:39], v[150:153], v[180:183], v[36:39]
	v_mfma_f32_16x16x32_bf16 v[4:7], v[172:175], v[180:183], v[4:7]
	v_mfma_f32_16x16x32_bf16 v[44:47], v[150:153], v[188:191], v[44:47]
	v_mfma_f32_16x16x32_bf16 v[12:15], v[172:175], v[188:191], v[12:15]
	v_mfma_f32_16x16x32_bf16 v[40:43], v[150:153], v[206:209], v[40:43]
	v_mfma_f32_16x16x32_bf16 v[8:11], v[172:175], v[206:209], v[8:11]
	v_mfma_f32_16x16x32_bf16 v[32:35], v[150:153], v[234:237], v[32:35]
	v_mfma_f32_16x16x32_bf16 v[0:3], v[172:175], v[234:237], v[0:3]
	s_barrier
	s_add_i32 vcc_lo, vcc_lo, 2
	s_add_u32 s26, s26, 0x100
	s_addc_u32 s27, s27, 0
	s_add_u32 s44, s44, 0x100
	s_addc_u32 s45, s45, 0
	s_cmp_gt_u32 vcc_lo, 29
	s_cbranch_scc0 .LBB1_939
	s_and_b64 vcc, exec, s[80:81]
	s_cbranch_vccz .LBB1_942
	s_barrier

.LBB1_1126:
	v_readlane_b32 s56, v253, 42
	v_readlane_b32 s1, v255, 43
	v_readlane_b32 s57, v253, 43
	s_add_i32 s1, s1, 9
	s_mov_b64 s[76:77], s[56:57]
	s_cmp_lt_i32 s1, s77
	v_readlane_b32 s2, v255, 45
	s_cselect_b64 s[16:17], -1, 0
	v_readlane_b32 s3, v255, 46
	s_and_b64 s[2:3], s[2:3], s[16:17]
	s_andn2_b64 vcc, exec, s[2:3]
	v_readlane_b32 s58, v253, 44
	v_readlane_b32 s59, v253, 45
	s_cbranch_vccnz .LBB1_1176
	s_setprio 0
	s_waitcnt vmcnt(0)
	s_waitcnt vmcnt(0) lgkmcnt(0)
	s_barrier
	s_mov_b64 s[2:3], exec
	v_readlane_b32 s6, v255, 20
	v_readlane_b32 s7, v255, 21
	s_and_b64 s[6:7], s[2:3], s[6:7]
	s_mov_b64 exec, s[6:7]
	s_cbranch_execz .LBB1_1175
	v_readlane_b32 s5, v255, 18
	s_waitcnt vmcnt(0) expcnt(0) lgkmcnt(0)
	buffer_inv sc1
	s_nop 0
	v_mov_b32_e32 v0, s5
	ds_read_b32 v2, v0
	v_readlane_b32 s5, v255, 19
	s_waitcnt lgkmcnt(0)
	v_cmp_ne_u32_e32 vcc, 0, v2
	v_mov_b32_e32 v0, s5
	ds_read_b32 v0, v0
	s_cbranch_vccnz .LBB1_1143
	v_readlane_b32 s10, v253, 8
	v_readlane_b32 s11, v253, 9
	s_load_dwordx2 s[6:7], s[10:11], 0x4
	s_waitcnt lgkmcnt(0)
	s_mul_i32 s5, s6, s33
	s_mul_i32 s5, s5, s7
	s_mov_b32 s6, 1
	s_branch .LBB1_1131

.LBB1_1186:
	s_or_b64 exec, exec, s[2:3]
	v_readlane_b32 s1, v255, 43
	s_add_i32 s1, s1, 10
	s_cmp_ge_i32 s1, s77
	s_cbranch_scc1 .LBB1_1236
	s_setprio 0
	s_waitcnt vmcnt(0)
	s_waitcnt vmcnt(0) lgkmcnt(0)
	s_barrier
	s_mov_b64 s[2:3], exec
	v_readlane_b32 s6, v255, 20
	v_readlane_b32 s7, v255, 21
	s_and_b64 s[6:7], s[2:3], s[6:7]
	s_mov_b64 exec, s[6:7]
	s_cbranch_execz .LBB1_1235
	v_readlane_b32 s5, v255, 18
	s_waitcnt vmcnt(0) expcnt(0) lgkmcnt(0)
	buffer_inv sc1
	s_nop 0
	v_mov_b32_e32 v0, s5
	ds_read_b32 v2, v0
	v_readlane_b32 s5, v255, 19
	s_waitcnt lgkmcnt(0)
	v_cmp_ne_u32_e32 vcc, 0, v2
	v_mov_b32_e32 v0, s5
	ds_read_b32 v0, v0
	s_cbranch_vccnz .LBB1_1203
	v_readlane_b32 s10, v253, 8
	v_readlane_b32 s11, v253, 9
	s_load_dwordx2 s[6:7], s[10:11], 0x4
	s_waitcnt lgkmcnt(0)
	s_mul_i32 s5, s6, s33
	s_mul_i32 s5, s5, s7
	s_mov_b32 s6, 1
	s_branch .LBB1_1191

.LBB1_1244:
	s_sext_i32_i8 s76, s17
	s_mul_hi_u32 s17, s30, 0x24000
	s_mul_i32 s30, s30, 0x24000
	v_readlane_b32 s31, v253, 51
	s_add_u32 s30, s31, s30
	v_readlane_b32 s31, v253, 52
	s_addc_u32 s31, s31, s17
	v_and_b32_e32 v17, 48, v14
	v_lshlrev_b32_e32 v18, 6, v14
	s_movk_i32 s17, 0x3c0
	v_lshlrev_b32_e32 v14, 2, v14
	s_and_b32 s37, s36, 3
	s_lshl_b32 s54, s16, 6
	s_lshl_b32 s16, s16, 13
	v_and_or_b32 v17, v18, s17, v17
	v_and_b32_e32 v14, 32, v14
	s_add_i32 m0, s10, 0x18000
	v_lshl_add_u64 v[6:7], v[6:7], 0, s[48:49]
	v_bitop3_b32 v18, v17, s16, v14 bitop3:0xde
	s_lshl_b32 s16, s37, 12
	s_waitcnt vmcnt(2)
	s_barrier
	global_load_lds_dwordx4 v[6:7], off
	v_lshl_add_u64 v[4:5], v[4:5], 0, s[48:49]
	s_add_i32 m0, s10, 0x1a000
	s_add_i32 s55, s10, 0x8000
	s_add_i32 s56, s10, 0xa000
	v_bitop3_b32 v146, v17, s16, v14 bitop3:0xde
	global_load_lds_dwordx4 v[4:5], off
	v_lshl_add_u64 v[0:1], v[0:1], 0, s[48:49]
	s_mov_b32 m0, s55
	s_add_u32 s16, s60, 0x58080
	global_load_lds_dwordx4 v[0:1], off
	v_lshl_add_u64 v[0:1], v[2:3], 0, s[48:49]
	s_mov_b32 m0, s56
	s_addc_u32 s17, s61, 0
	global_load_lds_dwordx4 v[0:1], off
	s_add_i32 m0, s10, 0x1c000
	v_lshl_add_u64 v[0:1], s[16:17], 0, v[112:113]
	global_load_lds_dwordx4 v[0:1], off
	v_lshl_add_u64 v[0:1], s[16:17], 0, v[134:135]
	s_add_i32 m0, s10, 0x1e000
	s_movk_i32 s41, 0x1600
	global_load_lds_dwordx4 v[0:1], off
	s_cmp_lt_u32 s36, 4
	s_cbranch_scc0 .Lgp_6
	s_setprio 1
.Lgp_6:
	v_lshrrev_b32_e32 v1, 1, v8
	v_mul_lo_u32 v0, v10, s41
	s_mov_b32 s40, 0x16000
	s_cselect_b64 s[16:17], -1, 0
	s_lshl_b32 s57, s37, 6
	v_mad_u64_u32 v[0:1], s[36:37], v1, s40, v[0:1]
	v_or_b32_e32 v0, v0, v9
	v_add_lshl_u32 v0, v0, v11, 1
	v_mov_b32_e32 v1, v113
	s_mov_b64 s[42:43], 0x160080
	v_lshl_add_u64 v[136:137], v[0:1], 0, s[42:43]
	v_lshrrev_b32_e32 v1, 1, v12
	v_mul_lo_u32 v0, v15, s41
	v_mad_u64_u32 v[0:1], s[36:37], v1, s40, v[0:1]
	s_waitcnt vmcnt(6)
	v_or_b32_e32 v0, v0, v13
	v_add_lshl_u32 v0, v0, v16, 1
	v_mov_b32_e32 v1, v113
	v_lshl_add_u64 v[138:139], v[0:1], 0, s[42:43]
	s_mov_b32 s66, 0
	v_add_u32_e32 v147, 0, v18
	s_barrier
	s_branch .LBB1_1247

.LBB1_1254:
	s_add_u32 s60, s26, 0x100
	s_addc_u32 s61, s27, 0
	s_add_i32 s84, 0, 0x10000
	s_cmpk_eq_i32 s83, 0x54
	s_cselect_b32 s75, s77, s61
	s_cselect_b32 s74, s78, s60
	v_add_u32_e32 v144, s84, v146
	s_cselect_b32 s63, s79, s82
	s_cselect_b32 s62, s80, s81
	s_add_i32 s85, 0, 0x14000
	ds_read_b128 v[140:143], v144
	ds_read_b128 v[148:151], v144 offset:1024
	ds_read_b128 v[152:155], v144 offset:2048
	ds_read_b128 v[156:159], v144 offset:3072
	v_add_u32_e32 v144, s85, v146
	ds_read_b128 v[160:163], v144
	ds_read_b128 v[164:167], v144 offset:1024
	ds_read_b128 v[168:171], v144 offset:2048
	ds_read_b128 v[172:175], v144 offset:3072
	v_lshl_add_u64 v[144:145], s[26:27], 0, v[136:137]
	s_add_i32 m0, s10, 0xc000
	ds_read_b128 v[176:179], v147
	ds_read_b128 v[180:183], v147 offset:1024
	ds_read_b128 v[184:187], v147 offset:2048
	ds_read_b128 v[188:191], v147 offset:3072
	ds_read_b128 v[198:201], v147 offset:4096
	ds_read_b128 v[206:209], v147 offset:5120
	ds_read_b128 v[210:213], v147 offset:6144
	ds_read_b128 v[234:237], v147 offset:7168
	global_load_lds_dwordx4 v[144:145], off
	v_lshl_add_u64 v[144:145], s[26:27], 0, v[138:139]
	s_add_i32 m0, s10, 0xe000
	s_nop 0
	global_load_lds_dwordx4 v[144:145], off
	s_waitcnt vmcnt(8)
	s_waitcnt lgkmcnt(0)
	s_barrier
	s_waitcnt lgkmcnt(0)
	v_mfma_f32_16x16x32_bf16 v[126:129], v[140:143], v[176:179], v[126:129]
	v_mfma_f32_16x16x32_bf16 v[122:125], v[152:155], v[176:179], v[122:125]
	v_mfma_f32_16x16x32_bf16 v[108:111], v[140:143], v[184:187], v[108:111]
	v_mfma_f32_16x16x32_bf16 v[104:107], v[152:155], v[184:187], v[104:107]
	v_mfma_f32_16x16x32_bf16 v[92:95], v[140:143], v[198:201], v[92:95]
	v_mfma_f32_16x16x32_bf16 v[88:91], v[152:155], v[198:201], v[88:91]
	v_mfma_f32_16x16x32_bf16 v[76:79], v[140:143], v[210:213], v[76:79]
	v_mfma_f32_16x16x32_bf16 v[72:75], v[152:155], v[210:213], v[72:75]
	v_mfma_f32_16x16x32_bf16 v[126:129], v[148:151], v[180:183], v[126:129]
	v_mfma_f32_16x16x32_bf16 v[122:125], v[156:159], v[180:183], v[122:125]
	v_mfma_f32_16x16x32_bf16 v[108:111], v[148:151], v[188:191], v[108:111]
	v_mfma_f32_16x16x32_bf16 v[104:107], v[156:159], v[188:191], v[104:107]
	v_mfma_f32_16x16x32_bf16 v[92:95], v[148:151], v[206:209], v[92:95]
	v_mfma_f32_16x16x32_bf16 v[88:91], v[156:159], v[206:209], v[88:91]
	v_mfma_f32_16x16x32_bf16 v[76:79], v[148:151], v[234:237], v[76:79]
	v_mfma_f32_16x16x32_bf16 v[72:75], v[156:159], v[234:237], v[72:75]
	v_mfma_f32_16x16x32_bf16 v[118:121], v[160:163], v[176:179], v[118:121]
	v_mfma_f32_16x16x32_bf16 v[114:117], v[168:171], v[176:179], v[114:117]
	v_mfma_f32_16x16x32_bf16 v[100:103], v[160:163], v[184:187], v[100:103]
	v_mfma_f32_16x16x32_bf16 v[96:99], v[168:171], v[184:187], v[96:99]
	v_mfma_f32_16x16x32_bf16 v[84:87], v[160:163], v[198:201], v[84:87]
	v_mfma_f32_16x16x32_bf16 v[80:83], v[168:171], v[198:201], v[80:83]
	v_mfma_f32_16x16x32_bf16 v[68:71], v[160:163], v[210:213], v[68:71]
	v_mfma_f32_16x16x32_bf16 v[64:67], v[168:171], v[210:213], v[64:67]
	v_mfma_f32_16x16x32_bf16 v[118:121], v[164:167], v[180:183], v[118:121]
	v_mfma_f32_16x16x32_bf16 v[114:117], v[172:175], v[180:183], v[114:117]
	v_mfma_f32_16x16x32_bf16 v[100:103], v[164:167], v[188:191], v[100:103]
	v_mfma_f32_16x16x32_bf16 v[96:99], v[172:175], v[188:191], v[96:99]
	v_mfma_f32_16x16x32_bf16 v[84:87], v[164:167], v[206:209], v[84:87]
	v_mfma_f32_16x16x32_bf16 v[80:83], v[172:175], v[206:209], v[80:83]
	v_mfma_f32_16x16x32_bf16 v[68:71], v[164:167], v[234:237], v[68:71]
	v_mfma_f32_16x16x32_bf16 v[64:67], v[172:175], v[234:237], v[64:67]
	s_barrier
	s_add_i32 s26, s84, s9
	v_lshl_add_u64 v[144:145], s[62:63], 0, v[112:113]
	s_mov_b32 m0, s26
	ds_read_b128 v[176:179], v147 offset:16384
	ds_read_b128 v[180:183], v147 offset:17408
	ds_read_b128 v[184:187], v147 offset:18432
	ds_read_b128 v[188:191], v147 offset:19456
	ds_read_b128 v[198:201], v147 offset:20480
	ds_read_b128 v[206:209], v147 offset:21504
	ds_read_b128 v[210:213], v147 offset:22528
	ds_read_b128 v[234:237], v147 offset:23552
	global_load_lds_dwordx4 v[144:145], off
	s_add_i32 m0, s26, 0x2000
	s_add_u32 s26, s62, 0x58000
	v_lshl_add_u64 v[192:193], s[62:63], 0, v[134:135]
	s_addc_u32 s27, s63, 0
	s_add_i32 s84, s85, s9
	global_load_lds_dwordx4 v[192:193], off
	v_lshl_add_u64 v[238:239], s[26:27], 0, v[112:113]
	s_mov_b32 m0, s84
	v_lshl_add_u64 v[240:241], s[74:75], 0, v[132:133]
	global_load_lds_dwordx4 v[238:239], off
	v_lshl_add_u64 v[238:239], s[26:27], 0, v[134:135]
	s_add_i32 m0, s84, 0x2000
	s_nop 0
	global_load_lds_dwordx4 v[238:239], off
	v_lshl_add_u64 v[238:239], s[74:75], 0, v[130:131]
	s_mov_b32 m0, s10
	s_nop 0
	global_load_lds_dwordx4 v[238:239], off
	s_mov_b32 m0, s11
	s_nop 0
	global_load_lds_dwordx4 v[240:241], off
	s_waitcnt vmcnt(8)
	s_waitcnt lgkmcnt(0)
	s_barrier
	s_waitcnt lgkmcnt(0)
	v_mfma_f32_16x16x32_bf16 v[60:63], v[140:143], v[176:179], v[60:63]
	v_mfma_f32_16x16x32_bf16 v[56:59], v[152:155], v[176:179], v[56:59]
	v_mfma_f32_16x16x32_bf16 v[44:47], v[140:143], v[184:187], v[44:47]
	v_mfma_f32_16x16x32_bf16 v[40:43], v[152:155], v[184:187], v[40:43]
	v_mfma_f32_16x16x32_bf16 v[28:31], v[140:143], v[198:201], v[28:31]
	v_mfma_f32_16x16x32_bf16 v[24:27], v[152:155], v[198:201], v[24:27]
	v_mfma_f32_16x16x32_bf16 v[12:15], v[140:143], v[210:213], v[12:15]
	v_mfma_f32_16x16x32_bf16 v[8:11], v[152:155], v[210:213], v[8:11]
	v_mfma_f32_16x16x32_bf16 v[60:63], v[148:151], v[180:183], v[60:63]
	v_mfma_f32_16x16x32_bf16 v[56:59], v[156:159], v[180:183], v[56:59]
	v_mfma_f32_16x16x32_bf16 v[44:47], v[148:151], v[188:191], v[44:47]
	v_mfma_f32_16x16x32_bf16 v[40:43], v[156:159], v[188:191], v[40:43]
	v_mfma_f32_16x16x32_bf16 v[28:31], v[148:151], v[206:209], v[28:31]
	v_mfma_f32_16x16x32_bf16 v[24:27], v[156:159], v[206:209], v[24:27]
	v_mfma_f32_16x16x32_bf16 v[12:15], v[148:151], v[234:237], v[12:15]
	v_mfma_f32_16x16x32_bf16 v[8:11], v[156:159], v[234:237], v[8:11]
	v_mfma_f32_16x16x32_bf16 v[52:55], v[160:163], v[176:179], v[52:55]
	v_mfma_f32_16x16x32_bf16 v[48:51], v[168:171], v[176:179], v[48:51]
	v_mfma_f32_16x16x32_bf16 v[36:39], v[160:163], v[184:187], v[36:39]
	v_mfma_f32_16x16x32_bf16 v[32:35], v[168:171], v[184:187], v[32:35]
	v_mfma_f32_16x16x32_bf16 v[20:23], v[160:163], v[198:201], v[20:23]
	v_mfma_f32_16x16x32_bf16 v[16:19], v[168:171], v[198:201], v[16:19]
	v_mfma_f32_16x16x32_bf16 v[4:7], v[160:163], v[210:213], v[4:7]
	v_mfma_f32_16x16x32_bf16 v[0:3], v[168:171], v[210:213], v[0:3]
	v_mfma_f32_16x16x32_bf16 v[52:55], v[164:167], v[180:183], v[52:55]
	v_mfma_f32_16x16x32_bf16 v[48:51], v[172:175], v[180:183], v[48:51]
	v_mfma_f32_16x16x32_bf16 v[36:39], v[164:167], v[188:191], v[36:39]
	v_mfma_f32_16x16x32_bf16 v[32:35], v[172:175], v[188:191], v[32:35]
	v_mfma_f32_16x16x32_bf16 v[20:23], v[164:167], v[206:209], v[20:23]
	v_mfma_f32_16x16x32_bf16 v[16:19], v[172:175], v[206:209], v[16:19]
	v_mfma_f32_16x16x32_bf16 v[4:7], v[164:167], v[234:237], v[4:7]
	v_mfma_f32_16x16x32_bf16 v[0:3], v[172:175], v[234:237], v[0:3]
	s_barrier
	s_add_i32 s84, 0, 0x18000
	s_add_i32 s85, 0, 0x1c000
	v_add_u32_e32 v156, s84, v146
	v_add_u32_e32 v172, s85, v146
	ds_read_b128 v[140:143], v156
	ds_read_b128 v[148:151], v156 offset:1024
	ds_read_b128 v[152:155], v156 offset:2048
	ds_read_b128 v[156:159], v156 offset:3072
	ds_read_b128 v[160:163], v172
	ds_read_b128 v[164:167], v172 offset:1024
	ds_read_b128 v[168:171], v172 offset:2048
	ds_read_b128 v[172:175], v172 offset:3072
	s_add_u32 s26, s74, 0x160000
	s_addc_u32 s27, s75, 0
	s_mov_b32 m0, s24
	v_lshl_add_u64 v[242:243], s[26:27], 0, v[130:131]
	ds_read_b128 v[176:179], v147 offset:32768
	ds_read_b128 v[180:183], v147 offset:33792
	ds_read_b128 v[184:187], v147 offset:34816
	ds_read_b128 v[188:191], v147 offset:35840
	ds_read_b128 v[198:201], v147 offset:36864
	ds_read_b128 v[206:209], v147 offset:37888
	ds_read_b128 v[210:213], v147 offset:38912
	ds_read_b128 v[234:237], v147 offset:39936
	global_load_lds_dwordx4 v[242:243], off
	v_lshl_add_u64 v[242:243], s[26:27], 0, v[132:133]
	s_mov_b32 m0, s25
	s_nop 0
	global_load_lds_dwordx4 v[242:243], off
	s_waitcnt vmcnt(8)
	s_waitcnt lgkmcnt(0)
	s_barrier
	s_waitcnt lgkmcnt(0)
	v_mfma_f32_16x16x32_bf16 v[126:129], v[140:143], v[176:179], v[126:129]
	v_mfma_f32_16x16x32_bf16 v[122:125], v[152:155], v[176:179], v[122:125]
	v_mfma_f32_16x16x32_bf16 v[108:111], v[140:143], v[184:187], v[108:111]
	v_mfma_f32_16x16x32_bf16 v[104:107], v[152:155], v[184:187], v[104:107]
	v_mfma_f32_16x16x32_bf16 v[92:95], v[140:143], v[198:201], v[92:95]
	v_mfma_f32_16x16x32_bf16 v[88:91], v[152:155], v[198:201], v[88:91]
	v_mfma_f32_16x16x32_bf16 v[76:79], v[140:143], v[210:213], v[76:79]
	v_mfma_f32_16x16x32_bf16 v[72:75], v[152:155], v[210:213], v[72:75]
	v_mfma_f32_16x16x32_bf16 v[126:129], v[148:151], v[180:183], v[126:129]
	v_mfma_f32_16x16x32_bf16 v[122:125], v[156:159], v[180:183], v[122:125]
	v_mfma_f32_16x16x32_bf16 v[108:111], v[148:151], v[188:191], v[108:111]
	v_mfma_f32_16x16x32_bf16 v[104:107], v[156:159], v[188:191], v[104:107]
	v_mfma_f32_16x16x32_bf16 v[92:95], v[148:151], v[206:209], v[92:95]
	v_mfma_f32_16x16x32_bf16 v[88:91], v[156:159], v[206:209], v[88:91]
	v_mfma_f32_16x16x32_bf16 v[76:79], v[148:151], v[234:237], v[76:79]
	v_mfma_f32_16x16x32_bf16 v[72:75], v[156:159], v[234:237], v[72:75]
	v_mfma_f32_16x16x32_bf16 v[118:121], v[160:163], v[176:179], v[118:121]
	v_mfma_f32_16x16x32_bf16 v[114:117], v[168:171], v[176:179], v[114:117]
	v_mfma_f32_16x16x32_bf16 v[100:103], v[160:163], v[184:187], v[100:103]
	v_mfma_f32_16x16x32_bf16 v[96:99], v[168:171], v[184:187], v[96:99]
	v_mfma_f32_16x16x32_bf16 v[84:87], v[160:163], v[198:201], v[84:87]
	v_mfma_f32_16x16x32_bf16 v[80:83], v[168:171], v[198:201], v[80:83]
	v_mfma_f32_16x16x32_bf16 v[68:71], v[160:163], v[210:213], v[68:71]
	v_mfma_f32_16x16x32_bf16 v[64:67], v[168:171], v[210:213], v[64:67]
	v_mfma_f32_16x16x32_bf16 v[118:121], v[164:167], v[180:183], v[118:121]
	v_mfma_f32_16x16x32_bf16 v[114:117], v[172:175], v[180:183], v[114:117]
	v_mfma_f32_16x16x32_bf16 v[100:103], v[164:167], v[188:191], v[100:103]
	v_mfma_f32_16x16x32_bf16 v[96:99], v[172:175], v[188:191], v[96:99]
	v_mfma_f32_16x16x32_bf16 v[84:87], v[164:167], v[206:209], v[84:87]
	v_mfma_f32_16x16x32_bf16 v[80:83], v[172:175], v[206:209], v[80:83]
	v_mfma_f32_16x16x32_bf16 v[68:71], v[164:167], v[234:237], v[68:71]
	v_mfma_f32_16x16x32_bf16 v[64:67], v[172:175], v[234:237], v[64:67]
	s_barrier
	s_add_i32 s26, s84, s9
	v_lshl_add_u64 v[144:145], v[144:145], 0, s[48:49]
	s_mov_b32 m0, s26
	ds_read_b128 v[176:179], v147 offset:49152
	ds_read_b128 v[180:183], v147 offset:50176
	ds_read_b128 v[184:187], v147 offset:51200
	ds_read_b128 v[188:191], v147 offset:52224
	ds_read_b128 v[198:201], v147 offset:53248
	ds_read_b128 v[206:209], v147 offset:54272
	ds_read_b128 v[210:213], v147 offset:55296
	ds_read_b128 v[234:237], v147 offset:56320
	global_load_lds_dwordx4 v[144:145], off
	s_add_i32 m0, s26, 0x2000
	s_add_u32 s26, s62, 0x58080
	v_lshl_add_u64 v[144:145], v[192:193], 0, s[48:49]
	s_addc_u32 s27, s63, 0
	s_add_i32 s62, s85, s9
	global_load_lds_dwordx4 v[144:145], off
	v_lshl_add_u64 v[144:145], s[26:27], 0, v[112:113]
	s_mov_b32 m0, s62
	s_nop 0
	global_load_lds_dwordx4 v[144:145], off
	v_lshl_add_u64 v[144:145], s[26:27], 0, v[134:135]
	s_add_i32 m0, s62, 0x2000
	s_nop 0
	global_load_lds_dwordx4 v[144:145], off
	v_lshl_add_u64 v[144:145], v[238:239], 0, s[48:49]
	s_mov_b32 m0, s55
	s_nop 0
	global_load_lds_dwordx4 v[144:145], off
	v_lshl_add_u64 v[144:145], v[240:241], 0, s[48:49]
	s_mov_b32 m0, s56
	s_nop 0
	global_load_lds_dwordx4 v[144:145], off
	s_waitcnt vmcnt(8)
	s_waitcnt lgkmcnt(0)
	s_barrier
	s_waitcnt lgkmcnt(0)
	v_mfma_f32_16x16x32_bf16 v[60:63], v[140:143], v[176:179], v[60:63]
	v_mfma_f32_16x16x32_bf16 v[56:59], v[152:155], v[176:179], v[56:59]
	v_mfma_f32_16x16x32_bf16 v[44:47], v[140:143], v[184:187], v[44:47]
	v_mfma_f32_16x16x32_bf16 v[40:43], v[152:155], v[184:187], v[40:43]
	v_mfma_f32_16x16x32_bf16 v[28:31], v[140:143], v[198:201], v[28:31]
	v_mfma_f32_16x16x32_bf16 v[24:27], v[152:155], v[198:201], v[24:27]
	v_mfma_f32_16x16x32_bf16 v[12:15], v[140:143], v[210:213], v[12:15]
	v_mfma_f32_16x16x32_bf16 v[8:11], v[152:155], v[210:213], v[8:11]
	v_mfma_f32_16x16x32_bf16 v[60:63], v[148:151], v[180:183], v[60:63]
	v_mfma_f32_16x16x32_bf16 v[56:59], v[156:159], v[180:183], v[56:59]
	v_mfma_f32_16x16x32_bf16 v[44:47], v[148:151], v[188:191], v[44:47]
	v_mfma_f32_16x16x32_bf16 v[40:43], v[156:159], v[188:191], v[40:43]
	v_mfma_f32_16x16x32_bf16 v[28:31], v[148:151], v[206:209], v[28:31]
	v_mfma_f32_16x16x32_bf16 v[24:27], v[156:159], v[206:209], v[24:27]
	v_mfma_f32_16x16x32_bf16 v[12:15], v[148:151], v[234:237], v[12:15]
	v_mfma_f32_16x16x32_bf16 v[8:11], v[156:159], v[234:237], v[8:11]
	v_mfma_f32_16x16x32_bf16 v[52:55], v[160:163], v[176:179], v[52:55]
	v_mfma_f32_16x16x32_bf16 v[48:51], v[168:171], v[176:179], v[48:51]
	v_mfma_f32_16x16x32_bf16 v[36:39], v[160:163], v[184:187], v[36:39]
	v_mfma_f32_16x16x32_bf16 v[32:35], v[168:171], v[184:187], v[32:35]
	v_mfma_f32_16x16x32_bf16 v[20:23], v[160:163], v[198:201], v[20:23]
	v_mfma_f32_16x16x32_bf16 v[16:19], v[168:171], v[198:201], v[16:19]
	v_mfma_f32_16x16x32_bf16 v[4:7], v[160:163], v[210:213], v[4:7]
	v_mfma_f32_16x16x32_bf16 v[0:3], v[168:171], v[210:213], v[0:3]
	v_mfma_f32_16x16x32_bf16 v[52:55], v[164:167], v[180:183], v[52:55]
	v_mfma_f32_16x16x32_bf16 v[48:51], v[172:175], v[180:183], v[48:51]
	v_mfma_f32_16x16x32_bf16 v[36:39], v[164:167], v[188:191], v[36:39]
	v_mfma_f32_16x16x32_bf16 v[32:35], v[172:175], v[188:191], v[32:35]
	v_mfma_f32_16x16x32_bf16 v[20:23], v[164:167], v[206:209], v[20:23]
	v_mfma_f32_16x16x32_bf16 v[16:19], v[172:175], v[206:209], v[16:19]
	v_mfma_f32_16x16x32_bf16 v[4:7], v[164:167], v[234:237], v[4:7]
	v_mfma_f32_16x16x32_bf16 v[0:3], v[172:175], v[234:237], v[0:3]
	s_barrier
	s_add_i32 s83, s83, 2
	s_add_u32 s81, s81, 0x100
	s_addc_u32 s82, s82, 0
	s_cmpk_gt_u32 s83, 0x55
	s_mov_b64 s[26:27], s[60:61]
	s_cbranch_scc0 .LBB1_1254
	s_and_b64 vcc, exec, s[16:17]
	s_cbranch_vccz .LBB1_1257
	s_barrier

.LBB1_1269:
	s_setprio 0
	s_waitcnt vmcnt(0)
	s_waitcnt vmcnt(0) lgkmcnt(0)
	s_barrier
	s_mov_b64 s[2:3], exec
	v_readlane_b32 s6, v255, 20
	v_readlane_b32 s7, v255, 21
	s_and_b64 s[6:7], s[2:3], s[6:7]
	s_mov_b64 exec, s[6:7]
	s_cbranch_execnz .LBB1_1270
	s_getpc_b64 s[98:99]
